# c2 plus blocked memory layout for the MLP hidden activations U (1-KiB blocks of 16 rows x 32 cols): MLP-up epilogue stores and MLP-down A-operand LDS-DMA loads become contiguous full cache lines per i
# speedup vs baseline: 1.0145x; 1.0104x over previous
; __device__ __forceinline__ unsigned cvt_pk_bf16(float lo, float hi) { unsigned r; asm volatile("v_cvt_pk_bf16_f32 %0, %1, %2" : "=v"(r) : "v"(lo), "v"(hi)); return r; }
;     __device__ __forceinline__ void operator()(const AccT& acc, const Unit& u, int wr, int wc, int fr, int fq) const {
;     ...
;         for (int ai = 0; ai < 2; ++ai)
; #pragma unroll
;             for (int m = 0; m < 4; ++m) { bf16_t* rowp = U + (size_t)(row0 + ai * 128 + m * 16) * FF + col0;
;                 const float rstd = rs[ai * 4 + m];
; #pragma unroll
;                 for (int bj = 0; bj < 2; ++bj) { f32x4 v0 = acc[ai][bj][m][0], v1 = acc[ai][bj][m][1];
; #pragma unroll
;                     for (int j = 0; j < 4; ++j) { const float a = fmaxf(v0[j], 0.f) * rstd, b = fmaxf(v1[j], 0.f) * rstd; v0[j] = a * a; v1[j] = b * b; }
;                     u32x4 w; w.x = cvt_pk_bf16(v0[0], v0[1]); w.y = cvt_pk_bf16(v0[2], v0[3]); w.z = cvt_pk_bf16(v1[0], v1[1]); w.w = cvt_pk_bf16(v1[2], v1[3]);
;                     *(u32x4*)(rowp + bj * 128) = w; } }
.LBB0_782:
	ds_read2_b32 v[160:161], v157 offset1:16
	ds_read2_b32 v[146:147], v157 offset0:32 offset1:48
	ds_read2_b32 v[144:145], v158 offset1:16
	ds_read2_b32 v[140:141], v158 offset0:32 offset1:48
	v_max_f32_e32 v122, v122, v122
	v_add_u32_e32 v148, s13, v152
	v_max_f32_e32 v122, 0, v122
	v_max_f32_e32 v123, v123, v123
	v_max_f32_e32 v124, v124, v124
	v_ashrrev_i32_e32 v149, 31, v148
	s_waitcnt lgkmcnt(0)
	v_mul_f32_e32 v122, v122, v160
	v_max_f32_e32 v123, 0, v123
	v_max_f32_e32 v124, 0, v124
	v_and_b32_e32 v150, 0xfffffff0, v148
	v_mov_b32_e32 v151, 0
	v_lshlrev_b64 v[150:151], 14, v[150:151]
	v_mul_f32_e32 v149, v122, v122
	v_max_f32_e32 v122, v127, v127
	v_mul_f32_e32 v123, v123, v160
	v_mul_f32_e32 v124, v124, v160
	v_lshl_or_b32 v142, s36, 8, v154
	v_max_f32_e32 v126, v126, v126
	v_max_f32_e32 v122, 0, v122
	v_mul_f32_e32 v127, v123, v123
	v_max_f32_e32 v123, v128, v128
	v_mul_f32_e32 v128, v124, v124
	v_max_f32_e32 v124, v129, v129
	v_max_f32_e32 v125, v125, v125
	v_ashrrev_i32_e32 v143, 31, v142
	v_max_f32_e32 v126, 0, v126
	v_mul_f32_e32 v122, v122, v160
	v_max_f32_e32 v123, 0, v123
	v_max_f32_e32 v124, 0, v124
	v_max_f32_e32 v125, 0, v125
	v_max_f32_e32 v114, v114, v114
	v_max_f32_e32 v115, v115, v115
	v_max_f32_e32 v116, v116, v116
	v_lshl_add_u64 v[162:163], s[8:9], 0, v[150:151]
	v_lshrrev_b32_e32 v150, 5, v142
	v_lshlrev_b32_e32 v150, 10, v150
	v_and_b32_e32 v151, 31, v142
	v_lshl_add_u32 v150, v151, 1, v150
	v_and_b32_e32 v151, 15, v148
	v_lshl_add_u32 v150, v151, 6, v150
	v_add_u32_e32 v150, 0x800, v150
	v_mov_b32_e32 v151, 0
	v_mul_f32_e32 v126, v126, v160
	v_mul_f32_e32 v122, v122, v122
	v_mul_f32_e32 v123, v123, v160
	v_mul_f32_e32 v124, v124, v160
	v_mul_f32_e32 v125, v125, v160
	v_max_f32_e32 v114, 0, v114
	v_max_f32_e32 v115, 0, v115
	v_max_f32_e32 v116, 0, v116
	v_lshl_add_u64 v[142:143], v[162:163], 0, v[150:151]
	v_mul_f32_e32 v126, v126, v126
	v_mul_f32_e32 v123, v123, v123
	v_mul_f32_e32 v124, v124, v124
	v_mul_f32_e32 v125, v125, v125
	v_cvt_pk_bf16_f32 v122, v126, v122
	v_mul_f32_e32 v114, v114, v160
	v_mul_f32_e32 v115, v115, v160
	v_mul_f32_e32 v116, v116, v160
	v_cvt_pk_bf16_f32 v123, v123, v124
	v_cvt_pk_bf16_f32 v124, v149, v127
	v_cvt_pk_bf16_f32 v125, v128, v125
	global_store_dwordx4 v[142:143], v[122:125], off offset:-2048
	v_max_f32_e32 v118, v118, v118
	v_max_f32_e32 v117, v117, v117
	v_mul_f32_e32 v122, v114, v114
	v_max_f32_e32 v114, v119, v119
	v_mul_f32_e32 v119, v115, v115
	v_max_f32_e32 v115, v120, v120
	v_mul_f32_e32 v120, v116, v116
	v_max_f32_e32 v116, v121, v121
	v_max_f32_e32 v114, 0, v114
	v_max_f32_e32 v115, 0, v115
	v_max_f32_e32 v116, 0, v116
	v_max_f32_e32 v118, 0, v118
	v_mul_f32_e32 v114, v114, v160
	v_mul_f32_e32 v115, v115, v160
	v_mul_f32_e32 v116, v116, v160
	v_max_f32_e32 v117, 0, v117
	v_max_f32_e32 v106, v106, v106
	v_mul_f32_e32 v118, v118, v160
	v_mul_f32_e32 v114, v114, v114
	v_mul_f32_e32 v115, v115, v115
	v_mul_f32_e32 v117, v117, v160
	v_mul_f32_e32 v116, v116, v116
	v_max_f32_e32 v106, 0, v106
	v_max_f32_e32 v107, v107, v107
	v_max_f32_e32 v108, v108, v108
	v_mul_f32_e32 v118, v118, v118
	v_mul_f32_e32 v117, v117, v117
	v_cvt_pk_bf16_f32 v114, v118, v114
	v_cvt_pk_bf16_f32 v115, v115, v116
	v_cvt_pk_bf16_f32 v116, v122, v119
	v_mul_f32_e32 v106, v106, v161
	v_max_f32_e32 v107, 0, v107
	v_max_f32_e32 v108, 0, v108
	v_cvt_pk_bf16_f32 v117, v120, v117
	global_store_dwordx4 v[142:143], v[114:117], off offset:2048
	v_mul_f32_e32 v107, v107, v161
	v_mul_f32_e32 v108, v108, v161
	v_or_b32_e32 v114, 16, v148
	v_and_b32_e32 v114, 0xfffffff0, v114
	v_mul_f32_e32 v116, v106, v106
	v_max_f32_e32 v106, v111, v111
	v_ashrrev_i32_e32 v115, 31, v114
	v_max_f32_e32 v110, v110, v110
	v_max_f32_e32 v106, 0, v106
	v_mul_f32_e32 v111, v107, v107
	v_max_f32_e32 v107, v112, v112
	v_mul_f32_e32 v112, v108, v108
	v_max_f32_e32 v108, v113, v113
	v_max_f32_e32 v109, v109, v109
	v_lshlrev_b64 v[114:115], 14, v[114:115]
	v_max_f32_e32 v110, 0, v110
	v_mul_f32_e32 v106, v106, v161
	v_max_f32_e32 v107, 0, v107
	v_max_f32_e32 v108, 0, v108
	v_max_f32_e32 v109, 0, v109
	v_max_f32_e32 v98, v98, v98
	v_max_f32_e32 v99, v99, v99
	v_max_f32_e32 v100, v100, v100
	v_lshl_add_u64 v[114:115], s[8:9], 0, v[114:115]
	v_mul_f32_e32 v110, v110, v161
	v_mul_f32_e32 v106, v106, v106
	v_mul_f32_e32 v107, v107, v161
	v_mul_f32_e32 v108, v108, v161
	v_mul_f32_e32 v109, v109, v161
	v_max_f32_e32 v98, 0, v98
	v_max_f32_e32 v99, 0, v99
	v_max_f32_e32 v100, 0, v100
	v_lshl_add_u64 v[114:115], v[114:115], 0, v[150:151]
	v_mul_f32_e32 v110, v110, v110
	v_mul_f32_e32 v107, v107, v107
	v_mul_f32_e32 v108, v108, v108
	v_mul_f32_e32 v109, v109, v109
	v_cvt_pk_bf16_f32 v106, v110, v106
	v_mul_f32_e32 v98, v98, v161
	v_mul_f32_e32 v99, v99, v161
	v_mul_f32_e32 v100, v100, v161
	v_cvt_pk_bf16_f32 v107, v107, v108
	v_cvt_pk_bf16_f32 v108, v116, v111
	v_cvt_pk_bf16_f32 v109, v112, v109
	global_store_dwordx4 v[114:115], v[106:109], off offset:-2048
	v_max_f32_e32 v102, v102, v102
	v_max_f32_e32 v101, v101, v101
	v_mul_f32_e32 v106, v98, v98
	v_max_f32_e32 v98, v103, v103
	v_mul_f32_e32 v103, v99, v99
	v_max_f32_e32 v99, v104, v104
	v_mul_f32_e32 v104, v100, v100
	v_max_f32_e32 v100, v105, v105
	v_max_f32_e32 v98, 0, v98
	v_max_f32_e32 v99, 0, v99
	v_max_f32_e32 v100, 0, v100
	v_max_f32_e32 v102, 0, v102
	v_mul_f32_e32 v98, v98, v161
	v_mul_f32_e32 v99, v99, v161
	v_mul_f32_e32 v100, v100, v161
	v_max_f32_e32 v101, 0, v101
	v_max_f32_e32 v90, v90, v90
	v_mul_f32_e32 v102, v102, v161
	v_mul_f32_e32 v98, v98, v98
	v_mul_f32_e32 v99, v99, v99
	v_mul_f32_e32 v101, v101, v161
	v_mul_f32_e32 v100, v100, v100
	v_max_f32_e32 v90, 0, v90
; __device__ __forceinline__ unsigned cvt_pk_bf16(float lo, float hi) { unsigned r; asm volatile("v_cvt_pk_bf16_f32 %0, %1, %2" : "=v"(r) : "v"(lo), "v"(hi)); return r; }
;     __device__ __forceinline__ void operator()(const AccT& acc, const Unit& u, int wr, int wc, int fr, int fq) const {
;     ...
;         for (int ai = 0; ai < 2; ++ai)
; #pragma unroll
;             for (int m = 0; m < 4; ++m) { bf16_t* rowp = U + (size_t)(row0 + ai * 128 + m * 16) * FF + col0;
;                 const float rstd = rs[ai * 4 + m];
; #pragma unroll
;                 for (int bj = 0; bj < 2; ++bj) { f32x4 v0 = acc[ai][bj][m][0], v1 = acc[ai][bj][m][1];
; #pragma unroll
;                     for (int j = 0; j < 4; ++j) { const float a = fmaxf(v0[j], 0.f) * rstd, b = fmaxf(v1[j], 0.f) * rstd; v0[j] = a * a; v1[j] = b * b; }
;                     u32x4 w; w.x = cvt_pk_bf16(v0[0], v0[1]); w.y = cvt_pk_bf16(v0[2], v0[3]); w.z = cvt_pk_bf16(v1[0], v1[1]); w.w = cvt_pk_bf16(v1[2], v1[3]);
;                     *(u32x4*)(rowp + bj * 128) = w; } }
	v_max_f32_e32 v91, v91, v91
	v_max_f32_e32 v92, v92, v92
	v_mul_f32_e32 v102, v102, v102
	v_mul_f32_e32 v101, v101, v101
	v_cvt_pk_bf16_f32 v98, v102, v98
	v_cvt_pk_bf16_f32 v99, v99, v100
	v_cvt_pk_bf16_f32 v100, v106, v103
	v_mul_f32_e32 v90, v90, v146
	v_max_f32_e32 v91, 0, v91
	v_max_f32_e32 v92, 0, v92
	v_cvt_pk_bf16_f32 v101, v104, v101
	global_store_dwordx4 v[114:115], v[98:101], off offset:2048
	v_mul_f32_e32 v91, v91, v146
	v_mul_f32_e32 v92, v92, v146
	v_or_b32_e32 v98, 32, v148
	v_and_b32_e32 v98, 0xfffffff0, v98
	v_mul_f32_e32 v100, v90, v90
	v_max_f32_e32 v90, v95, v95
	v_ashrrev_i32_e32 v99, 31, v98
	v_max_f32_e32 v94, v94, v94
	v_max_f32_e32 v90, 0, v90
	v_mul_f32_e32 v95, v91, v91
	v_max_f32_e32 v91, v96, v96
	v_mul_f32_e32 v96, v92, v92
	v_max_f32_e32 v92, v97, v97
	v_max_f32_e32 v93, v93, v93
	v_lshlrev_b64 v[98:99], 14, v[98:99]
	v_max_f32_e32 v94, 0, v94
	v_mul_f32_e32 v90, v90, v146
	v_max_f32_e32 v91, 0, v91
	v_max_f32_e32 v92, 0, v92
	v_max_f32_e32 v93, 0, v93
	v_max_f32_e32 v82, v82, v82
	v_max_f32_e32 v83, v83, v83
	v_max_f32_e32 v84, v84, v84
	v_lshl_add_u64 v[98:99], s[8:9], 0, v[98:99]
	v_mul_f32_e32 v94, v94, v146
	v_mul_f32_e32 v90, v90, v90
	v_mul_f32_e32 v91, v91, v146
	v_mul_f32_e32 v92, v92, v146
	v_mul_f32_e32 v93, v93, v146
	v_max_f32_e32 v82, 0, v82
	v_max_f32_e32 v83, 0, v83
	v_max_f32_e32 v84, 0, v84
	v_lshl_add_u64 v[98:99], v[98:99], 0, v[150:151]
	v_mul_f32_e32 v94, v94, v94
	v_mul_f32_e32 v91, v91, v91
	v_mul_f32_e32 v92, v92, v92
	v_mul_f32_e32 v93, v93, v93
	v_cvt_pk_bf16_f32 v90, v94, v90
	v_mul_f32_e32 v82, v82, v146
	v_mul_f32_e32 v83, v83, v146
	v_mul_f32_e32 v84, v84, v146
	v_cvt_pk_bf16_f32 v91, v91, v92
	v_cvt_pk_bf16_f32 v92, v100, v95
	v_cvt_pk_bf16_f32 v93, v96, v93
	global_store_dwordx4 v[98:99], v[90:93], off offset:-2048
	v_max_f32_e32 v86, v86, v86
	v_max_f32_e32 v85, v85, v85
	v_mul_f32_e32 v90, v82, v82
	v_max_f32_e32 v82, v87, v87
	v_mul_f32_e32 v87, v83, v83
	v_max_f32_e32 v83, v88, v88
	v_mul_f32_e32 v88, v84, v84
	v_max_f32_e32 v84, v89, v89
	v_max_f32_e32 v82, 0, v82
	v_max_f32_e32 v83, 0, v83
	v_max_f32_e32 v84, 0, v84
	v_max_f32_e32 v86, 0, v86
	v_mul_f32_e32 v82, v82, v146
	v_mul_f32_e32 v83, v83, v146
	v_mul_f32_e32 v84, v84, v146
	v_max_f32_e32 v85, 0, v85
	v_max_f32_e32 v74, v74, v74
	v_mul_f32_e32 v86, v86, v146
	v_mul_f32_e32 v82, v82, v82
	v_mul_f32_e32 v83, v83, v83
	v_mul_f32_e32 v85, v85, v146
	v_mul_f32_e32 v84, v84, v84
	v_max_f32_e32 v74, 0, v74
	v_max_f32_e32 v75, v75, v75
	v_max_f32_e32 v76, v76, v76
	v_mul_f32_e32 v86, v86, v86
	v_mul_f32_e32 v85, v85, v85
	v_cvt_pk_bf16_f32 v82, v86, v82
	v_cvt_pk_bf16_f32 v83, v83, v84
	v_cvt_pk_bf16_f32 v84, v90, v87
	v_mul_f32_e32 v74, v74, v147
	v_max_f32_e32 v75, 0, v75
	v_max_f32_e32 v76, 0, v76
	v_cvt_pk_bf16_f32 v85, v88, v85
	global_store_dwordx4 v[98:99], v[82:85], off offset:2048
	v_mul_f32_e32 v75, v75, v147
	v_mul_f32_e32 v76, v76, v147
	v_or_b32_e32 v82, 48, v148
	v_and_b32_e32 v82, 0xfffffff0, v82
	v_mul_f32_e32 v84, v74, v74
	v_max_f32_e32 v74, v79, v79
	v_ashrrev_i32_e32 v83, 31, v82
	v_max_f32_e32 v78, v78, v78
	v_max_f32_e32 v74, 0, v74
	v_mul_f32_e32 v79, v75, v75
	v_max_f32_e32 v75, v80, v80
	v_mul_f32_e32 v80, v76, v76
	v_max_f32_e32 v76, v81, v81
	v_max_f32_e32 v77, v77, v77
	v_lshlrev_b64 v[82:83], 14, v[82:83]
	v_max_f32_e32 v78, 0, v78
	v_mul_f32_e32 v74, v74, v147
	v_max_f32_e32 v75, 0, v75
	v_max_f32_e32 v76, 0, v76
	v_max_f32_e32 v77, 0, v77
	v_max_f32_e32 v66, v66, v66
	v_max_f32_e32 v67, v67, v67
	v_max_f32_e32 v68, v68, v68
	v_lshl_add_u64 v[82:83], s[8:9], 0, v[82:83]
	v_mul_f32_e32 v78, v78, v147
	v_mul_f32_e32 v74, v74, v74
	v_mul_f32_e32 v75, v75, v147
	v_mul_f32_e32 v76, v76, v147
	v_mul_f32_e32 v77, v77, v147
	v_max_f32_e32 v66, 0, v66
	v_max_f32_e32 v67, 0, v67
	v_max_f32_e32 v68, 0, v68
	v_lshl_add_u64 v[82:83], v[82:83], 0, v[150:151]
	v_mul_f32_e32 v78, v78, v78
	v_mul_f32_e32 v75, v75, v75
	v_mul_f32_e32 v76, v76, v76
	v_mul_f32_e32 v77, v77, v77
	v_cvt_pk_bf16_f32 v74, v78, v74
	v_mul_f32_e32 v66, v66, v147
	v_mul_f32_e32 v67, v67, v147
	v_mul_f32_e32 v68, v68, v147
	v_cvt_pk_bf16_f32 v75, v75, v76
	v_cvt_pk_bf16_f32 v76, v84, v79
	v_cvt_pk_bf16_f32 v77, v80, v77
	global_store_dwordx4 v[82:83], v[74:77], off offset:-2048
	v_max_f32_e32 v70, v70, v70
	v_max_f32_e32 v69, v69, v69
	v_mul_f32_e32 v74, v66, v66
	v_max_f32_e32 v66, v71, v71
	v_mul_f32_e32 v71, v67, v67
	v_max_f32_e32 v67, v72, v72
	v_mul_f32_e32 v72, v68, v68
	v_max_f32_e32 v68, v73, v73
	v_max_f32_e32 v66, 0, v66
	v_max_f32_e32 v67, 0, v67
	v_max_f32_e32 v68, 0, v68
	v_max_f32_e32 v70, 0, v70
	v_mul_f32_e32 v66, v66, v147
	v_mul_f32_e32 v67, v67, v147
	v_mul_f32_e32 v68, v68, v147
	v_max_f32_e32 v69, 0, v69
	v_max_f32_e32 v58, v58, v58
	v_mul_f32_e32 v70, v70, v147
	v_mul_f32_e32 v66, v66, v66
	v_mul_f32_e32 v67, v67, v67
	v_mul_f32_e32 v69, v69, v147
	v_mul_f32_e32 v68, v68, v68
	v_max_f32_e32 v58, 0, v58
	v_max_f32_e32 v59, v59, v59
	v_max_f32_e32 v60, v60, v60
	v_mul_f32_e32 v70, v70, v70
	v_mul_f32_e32 v69, v69, v69
	v_cvt_pk_bf16_f32 v66, v70, v66
	v_cvt_pk_bf16_f32 v67, v67, v68
	v_cvt_pk_bf16_f32 v68, v74, v71
	v_mul_f32_e32 v58, v58, v144
	v_max_f32_e32 v59, 0, v59
	v_max_f32_e32 v60, 0, v60
	v_cvt_pk_bf16_f32 v69, v72, v69
	global_store_dwordx4 v[82:83], v[66:69], off offset:2048
	v_max_f32_e32 v62, v62, v62
	v_mul_f32_e32 v59, v59, v144
	v_mul_f32_e32 v68, v58, v58
	v_max_f32_e32 v58, v63, v63
	v_mul_f32_e32 v60, v60, v144
	v_max_f32_e32 v62, 0, v62
	v_max_f32_e32 v58, 0, v58
	v_mul_f32_e32 v63, v59, v59
	v_max_f32_e32 v59, v64, v64
	v_mul_f32_e32 v64, v60, v60
	v_max_f32_e32 v60, v65, v65
; __device__ __forceinline__ unsigned cvt_pk_bf16(float lo, float hi) { unsigned r; asm volatile("v_cvt_pk_bf16_f32 %0, %1, %2" : "=v"(r) : "v"(lo), "v"(hi)); return r; }
;     __device__ __forceinline__ void operator()(const AccT& acc, const Unit& u, int wr, int wc, int fr, int fq) const {
;     ...
;         for (int ai = 0; ai < 2; ++ai)
; #pragma unroll
;             for (int m = 0; m < 4; ++m) { bf16_t* rowp = U + (size_t)(row0 + ai * 128 + m * 16) * FF + col0;
;                 const float rstd = rs[ai * 4 + m];
; #pragma unroll
;                 for (int bj = 0; bj < 2; ++bj) { f32x4 v0 = acc[ai][bj][m][0], v1 = acc[ai][bj][m][1];
; #pragma unroll
;                     for (int j = 0; j < 4; ++j) { const float a = fmaxf(v0[j], 0.f) * rstd, b = fmaxf(v1[j], 0.f) * rstd; v0[j] = a * a; v1[j] = b * b; }
;                     u32x4 w; w.x = cvt_pk_bf16(v0[0], v0[1]); w.y = cvt_pk_bf16(v0[2], v0[3]); w.z = cvt_pk_bf16(v1[0], v1[1]); w.w = cvt_pk_bf16(v1[2], v1[3]);
;                     *(u32x4*)(rowp + bj * 128) = w; } }
	v_mul_f32_e32 v62, v62, v144
	v_mul_f32_e32 v58, v58, v144
	v_max_f32_e32 v59, 0, v59
	v_max_f32_e32 v60, 0, v60
	v_max_f32_e32 v61, v61, v61
	v_mul_f32_e32 v62, v62, v62
	v_mul_f32_e32 v58, v58, v58
	v_mul_f32_e32 v59, v59, v144
	v_mul_f32_e32 v60, v60, v144
	v_max_f32_e32 v61, 0, v61
	s_mov_b32 s13, 0x200000
	v_max_f32_e32 v50, v50, v50
	v_max_f32_e32 v51, v51, v51
	v_max_f32_e32 v52, v52, v52
	v_mul_f32_e32 v59, v59, v59
	v_mul_f32_e32 v61, v61, v144
	v_mul_f32_e32 v60, v60, v60
	v_cvt_pk_bf16_f32 v58, v62, v58
	v_add_co_u32_e32 v62, vcc, s13, v142
	v_max_f32_e32 v50, 0, v50
	v_max_f32_e32 v51, 0, v51
	v_max_f32_e32 v52, 0, v52
	v_mul_f32_e32 v61, v61, v61
	v_cvt_pk_bf16_f32 v59, v59, v60
	v_cvt_pk_bf16_f32 v60, v68, v63
	v_addc_co_u32_e32 v63, vcc, 0, v143, vcc
	v_mul_f32_e32 v50, v50, v144
	v_mul_f32_e32 v51, v51, v144
	v_mul_f32_e32 v52, v52, v144
	v_cvt_pk_bf16_f32 v61, v64, v61
	global_store_dwordx4 v[62:63], v[58:61], off offset:-2048
	v_max_f32_e32 v54, v54, v54
	v_max_f32_e32 v53, v53, v53
	v_mul_f32_e32 v58, v50, v50
	v_max_f32_e32 v50, v55, v55
	v_mul_f32_e32 v55, v51, v51
	v_max_f32_e32 v51, v56, v56
	v_mul_f32_e32 v56, v52, v52
	v_max_f32_e32 v52, v57, v57
	v_max_f32_e32 v50, 0, v50
	v_max_f32_e32 v51, 0, v51
	v_max_f32_e32 v52, 0, v52
	v_max_f32_e32 v54, 0, v54
	v_mul_f32_e32 v50, v50, v144
	v_mul_f32_e32 v51, v51, v144
	v_mul_f32_e32 v52, v52, v144
	v_max_f32_e32 v53, 0, v53
	v_max_f32_e32 v42, v42, v42
	s_mov_b64 s[20:21], 0x200000
	v_mul_f32_e32 v54, v54, v144
	v_mul_f32_e32 v50, v50, v50
	v_mul_f32_e32 v51, v51, v51
	v_mul_f32_e32 v53, v53, v144
	v_mul_f32_e32 v52, v52, v52
	v_max_f32_e32 v42, 0, v42
	v_max_f32_e32 v43, v43, v43
	v_max_f32_e32 v44, v44, v44
	v_lshl_add_u64 v[66:67], v[142:143], 0, s[20:21]
	v_mul_f32_e32 v54, v54, v54
	v_mul_f32_e32 v53, v53, v53
	v_cvt_pk_bf16_f32 v50, v54, v50
	v_cvt_pk_bf16_f32 v51, v51, v52
	v_cvt_pk_bf16_f32 v52, v58, v55
	v_mul_f32_e32 v42, v42, v145
	v_max_f32_e32 v43, 0, v43
	v_max_f32_e32 v44, 0, v44
	v_cvt_pk_bf16_f32 v53, v56, v53
	global_store_dwordx4 v[66:67], v[50:53], off offset:2048
	v_max_f32_e32 v46, v46, v46
	v_mul_f32_e32 v43, v43, v145
	v_mul_f32_e32 v52, v42, v42
	v_max_f32_e32 v42, v47, v47
	v_mul_f32_e32 v44, v44, v145
	v_max_f32_e32 v46, 0, v46
	v_max_f32_e32 v42, 0, v42
	v_mul_f32_e32 v47, v43, v43
	v_max_f32_e32 v43, v48, v48
	v_mul_f32_e32 v48, v44, v44
	v_max_f32_e32 v44, v49, v49
	v_mul_f32_e32 v46, v46, v145
	v_mul_f32_e32 v42, v42, v145
	v_max_f32_e32 v43, 0, v43
	v_max_f32_e32 v44, 0, v44
	v_max_f32_e32 v45, v45, v45
	v_mul_f32_e32 v46, v46, v46
	v_mul_f32_e32 v42, v42, v42
	v_mul_f32_e32 v43, v43, v145
	v_mul_f32_e32 v44, v44, v145
	v_max_f32_e32 v45, 0, v45
	s_mov_b32 s13, 0x240000
	v_max_f32_e32 v34, v34, v34
	v_max_f32_e32 v35, v35, v35
	v_max_f32_e32 v36, v36, v36
	v_mul_f32_e32 v43, v43, v43
	v_mul_f32_e32 v45, v45, v145
	v_mul_f32_e32 v44, v44, v44
	v_cvt_pk_bf16_f32 v42, v46, v42
	v_add_co_u32_e32 v46, vcc, s13, v142
	v_max_f32_e32 v34, 0, v34
	v_max_f32_e32 v35, 0, v35
	v_max_f32_e32 v36, 0, v36
	v_mul_f32_e32 v45, v45, v45
	v_cvt_pk_bf16_f32 v43, v43, v44
	v_cvt_pk_bf16_f32 v44, v52, v47
	v_addc_co_u32_e32 v47, vcc, 0, v143, vcc
	v_mul_f32_e32 v34, v34, v145
	v_mul_f32_e32 v35, v35, v145
	v_mul_f32_e32 v36, v36, v145
	v_cvt_pk_bf16_f32 v45, v48, v45
	global_store_dwordx4 v[46:47], v[42:45], off offset:-2048
	v_max_f32_e32 v38, v38, v38
	v_max_f32_e32 v37, v37, v37
	v_mul_f32_e32 v42, v34, v34
	v_max_f32_e32 v34, v39, v39
	v_mul_f32_e32 v39, v35, v35
	v_max_f32_e32 v35, v40, v40
	v_mul_f32_e32 v40, v36, v36
	v_max_f32_e32 v36, v41, v41
	v_max_f32_e32 v34, 0, v34
	v_max_f32_e32 v35, 0, v35
	v_max_f32_e32 v36, 0, v36
	v_max_f32_e32 v38, 0, v38
	v_mul_f32_e32 v34, v34, v145
	v_mul_f32_e32 v35, v35, v145
	v_mul_f32_e32 v36, v36, v145
	v_max_f32_e32 v37, 0, v37
	v_max_f32_e32 v26, v26, v26
	s_mov_b64 s[20:21], 0x240000
	v_mul_f32_e32 v38, v38, v145
	v_mul_f32_e32 v34, v34, v34
	v_mul_f32_e32 v35, v35, v35
	v_mul_f32_e32 v37, v37, v145
	v_mul_f32_e32 v36, v36, v36
	v_max_f32_e32 v26, 0, v26
	v_max_f32_e32 v27, v27, v27
	v_max_f32_e32 v28, v28, v28
	v_lshl_add_u64 v[50:51], v[142:143], 0, s[20:21]
	v_mul_f32_e32 v38, v38, v38
	v_mul_f32_e32 v37, v37, v37
	v_cvt_pk_bf16_f32 v34, v38, v34
	v_cvt_pk_bf16_f32 v35, v35, v36
	v_cvt_pk_bf16_f32 v36, v42, v39
	v_mul_f32_e32 v26, v26, v140
	v_max_f32_e32 v27, 0, v27
	v_max_f32_e32 v28, 0, v28
	v_cvt_pk_bf16_f32 v37, v40, v37
	global_store_dwordx4 v[50:51], v[34:37], off offset:2048
	v_max_f32_e32 v30, v30, v30
	v_mul_f32_e32 v27, v27, v140
	v_mul_f32_e32 v36, v26, v26
; __device__ __forceinline__ unsigned cvt_pk_bf16(float lo, float hi) { unsigned r; asm volatile("v_cvt_pk_bf16_f32 %0, %1, %2" : "=v"(r) : "v"(lo), "v"(hi)); return r; }
; #define PG8_BAR __builtin_amdgcn_s_barrier()
;     ...
;         if (!has_next) break;
; #pragma unroll
;         for (int a = 0; a < 2; ++a)
; #pragma unroll
;             for (int b = 0; b < 2; ++b)
; #pragma unroll
;                 for (int m = 0; m < 4; ++m)
; #pragma unroll
;                     for (int n = 0; n < 2; ++n) acc[a][b][m][n] = (f32x4){0.f, 0.f, 0.f, 0.f};
;         cur = nxt; cA = nA; cB = nB; ++ui;
;         if (wr == 1) PG8_BAR;
;     __device__ __forceinline__ void operator()(const AccT& acc, const Unit& u, int wr, int wc, int fr, int fq) const {
;     ...
;         for (int ai = 0; ai < 2; ++ai)
; #pragma unroll
;             for (int m = 0; m < 4; ++m) { bf16_t* rowp = U + (size_t)(row0 + ai * 128 + m * 16) * FF + col0;
;                 const float rstd = rs[ai * 4 + m];
; #pragma unroll
;                 for (int bj = 0; bj < 2; ++bj) { f32x4 v0 = acc[ai][bj][m][0], v1 = acc[ai][bj][m][1];
; #pragma unroll
;                     for (int j = 0; j < 4; ++j) { const float a = fmaxf(v0[j], 0.f) * rstd, b = fmaxf(v1[j], 0.f) * rstd; v0[j] = a * a; v1[j] = b * b; }
;                     u32x4 w; w.x = cvt_pk_bf16(v0[0], v0[1]); w.y = cvt_pk_bf16(v0[2], v0[3]); w.z = cvt_pk_bf16(v1[0], v1[1]); w.w = cvt_pk_bf16(v1[2], v1[3]);
;                     *(u32x4*)(rowp + bj * 128) = w; } }
	v_max_f32_e32 v26, v31, v31
	v_mul_f32_e32 v28, v28, v140
	v_max_f32_e32 v30, 0, v30
	v_max_f32_e32 v26, 0, v26
	v_mul_f32_e32 v31, v27, v27
	v_max_f32_e32 v27, v32, v32
	v_mul_f32_e32 v32, v28, v28
	v_max_f32_e32 v28, v33, v33
	v_mul_f32_e32 v30, v30, v140
	v_mul_f32_e32 v26, v26, v140
	v_max_f32_e32 v27, 0, v27
	v_max_f32_e32 v28, 0, v28
	v_max_f32_e32 v29, v29, v29
	v_mul_f32_e32 v30, v30, v30
	v_mul_f32_e32 v26, v26, v26
	v_mul_f32_e32 v27, v27, v140
	v_mul_f32_e32 v28, v28, v140
	v_max_f32_e32 v29, 0, v29
	s_mov_b32 s13, 0x280000
	v_max_f32_e32 v18, v18, v18
	v_max_f32_e32 v19, v19, v19
	v_max_f32_e32 v20, v20, v20
	v_mul_f32_e32 v27, v27, v27
	v_mul_f32_e32 v29, v29, v140
	v_mul_f32_e32 v28, v28, v28
	v_cvt_pk_bf16_f32 v26, v30, v26
	v_add_co_u32_e32 v30, vcc, s13, v142
	v_max_f32_e32 v18, 0, v18
	v_max_f32_e32 v19, 0, v19
	v_max_f32_e32 v20, 0, v20
	v_mul_f32_e32 v29, v29, v29
	v_cvt_pk_bf16_f32 v27, v27, v28
	v_cvt_pk_bf16_f32 v28, v36, v31
	v_addc_co_u32_e32 v31, vcc, 0, v143, vcc
	v_mul_f32_e32 v18, v18, v140
	v_mul_f32_e32 v19, v19, v140
	v_mul_f32_e32 v20, v20, v140
	v_cvt_pk_bf16_f32 v29, v32, v29
	global_store_dwordx4 v[30:31], v[26:29], off offset:-2048
	v_max_f32_e32 v22, v22, v22
	v_max_f32_e32 v21, v21, v21
	v_mul_f32_e32 v26, v18, v18
	v_max_f32_e32 v18, v23, v23
	v_mul_f32_e32 v23, v19, v19
	v_max_f32_e32 v19, v24, v24
	v_mul_f32_e32 v24, v20, v20
	v_max_f32_e32 v20, v25, v25
	v_max_f32_e32 v18, 0, v18
	v_max_f32_e32 v19, 0, v19
	v_max_f32_e32 v20, 0, v20
	v_max_f32_e32 v22, 0, v22
	v_mul_f32_e32 v18, v18, v140
	v_mul_f32_e32 v19, v19, v140
	v_mul_f32_e32 v20, v20, v140
	v_max_f32_e32 v21, 0, v21
	v_max_f32_e32 v10, v10, v10
	s_mov_b64 s[20:21], 0x280000
	v_mul_f32_e32 v22, v22, v140
	v_mul_f32_e32 v18, v18, v18
	v_mul_f32_e32 v19, v19, v19
	v_mul_f32_e32 v21, v21, v140
	v_mul_f32_e32 v20, v20, v20
	v_max_f32_e32 v10, 0, v10
	v_max_f32_e32 v11, v11, v11
	v_max_f32_e32 v12, v12, v12
	v_lshl_add_u64 v[34:35], v[142:143], 0, s[20:21]
	v_mul_f32_e32 v22, v22, v22
	v_mul_f32_e32 v21, v21, v21
	v_cvt_pk_bf16_f32 v18, v22, v18
	v_cvt_pk_bf16_f32 v19, v19, v20
	v_cvt_pk_bf16_f32 v20, v26, v23
	v_mul_f32_e32 v10, v10, v141
	v_max_f32_e32 v11, 0, v11
	v_max_f32_e32 v12, 0, v12
	v_cvt_pk_bf16_f32 v21, v24, v21
	global_store_dwordx4 v[34:35], v[18:21], off offset:2048
	v_max_f32_e32 v14, v14, v14
	v_mul_f32_e32 v11, v11, v141
	v_mul_f32_e32 v20, v10, v10
	v_max_f32_e32 v10, v15, v15
	v_mul_f32_e32 v12, v12, v141
	v_max_f32_e32 v14, 0, v14
	v_max_f32_e32 v10, 0, v10
	v_mul_f32_e32 v15, v11, v11
	v_max_f32_e32 v11, v16, v16
	v_mul_f32_e32 v16, v12, v12
	v_max_f32_e32 v12, v17, v17
	v_mul_f32_e32 v14, v14, v141
	v_mul_f32_e32 v10, v10, v141
	v_max_f32_e32 v11, 0, v11
	v_max_f32_e32 v12, 0, v12
	v_max_f32_e32 v13, v13, v13
	v_mul_f32_e32 v14, v14, v14
	v_mul_f32_e32 v10, v10, v10
	v_mul_f32_e32 v11, v11, v141
	v_mul_f32_e32 v12, v12, v141
	v_max_f32_e32 v13, 0, v13
	s_mov_b32 s13, 0x2c0000
	v_max_f32_e32 v2, v2, v2
	v_max_f32_e32 v3, v3, v3
	v_max_f32_e32 v4, v4, v4
	v_mul_f32_e32 v11, v11, v11
	v_mul_f32_e32 v13, v13, v141
	v_mul_f32_e32 v12, v12, v12
	v_cvt_pk_bf16_f32 v10, v14, v10
	v_add_co_u32_e32 v14, vcc, s13, v142
	v_max_f32_e32 v2, 0, v2
	v_max_f32_e32 v3, 0, v3
	v_max_f32_e32 v4, 0, v4
	v_mul_f32_e32 v13, v13, v13
	v_cvt_pk_bf16_f32 v11, v11, v12
	v_cvt_pk_bf16_f32 v12, v20, v15
	v_addc_co_u32_e32 v15, vcc, 0, v143, vcc
	v_mul_f32_e32 v2, v2, v141
	v_mul_f32_e32 v3, v3, v141
	v_mul_f32_e32 v4, v4, v141
	v_cvt_pk_bf16_f32 v13, v16, v13
	global_store_dwordx4 v[14:15], v[10:13], off offset:-2048
	v_max_f32_e32 v5, v5, v5
	v_max_f32_e32 v6, v6, v6
	v_mul_f32_e32 v10, v2, v2
	v_max_f32_e32 v2, v7, v7
	v_mul_f32_e32 v7, v3, v3
	v_max_f32_e32 v3, v8, v8
	v_mul_f32_e32 v8, v4, v4
	v_max_f32_e32 v4, v9, v9
	v_max_f32_e32 v2, 0, v2
	v_max_f32_e32 v3, 0, v3
	v_max_f32_e32 v4, 0, v4
	v_max_f32_e32 v5, 0, v5
	s_mov_b64 s[20:21], 0x2c0000
	v_max_f32_e32 v6, 0, v6
	v_mul_f32_e32 v2, v2, v141
	v_mul_f32_e32 v3, v3, v141
	v_mul_f32_e32 v4, v4, v141
	v_mul_f32_e32 v5, v5, v141
	v_lshl_add_u64 v[18:19], v[142:143], 0, s[20:21]
	v_mul_f32_e32 v6, v6, v141
	v_mul_f32_e32 v2, v2, v2
	v_mul_f32_e32 v3, v3, v3
	v_mul_f32_e32 v4, v4, v4
	v_mul_f32_e32 v5, v5, v5
	s_andn2_b64 vcc, exec, s[44:45]
	s_mov_b64 s[20:21], -1
	v_mul_f32_e32 v6, v6, v6
	v_cvt_pk_bf16_f32 v2, v6, v2
	v_cvt_pk_bf16_f32 v3, v3, v4
	v_cvt_pk_bf16_f32 v4, v10, v7
	v_cvt_pk_bf16_f32 v5, v8, v5
	global_store_dwordx4 v[18:19], v[2:5], off offset:2048
	s_cbranch_vccnz .LBB0_766
	s_andn2_b64 vcc, exec, s[6:7]
	s_cbranch_vccnz .LBB0_765
	s_barrier
	s_branch .LBB0_765

; #define LAS __attribute__((address_space(3)))
; #define ARGS() KArgs* ap = (KArgs*)__builtin_amdgcn_kernarg_segment_ptr(); asm volatile("" : "+s"(ap)); unsigned char* ws = ap->ws; (void)ws
; __global__ void __launch_bounds__(512, 2) fwd_megakernel(Args a_unused) {
;     ...
;         } else {
;             ARGS();
;             pg8::Gemm g{(const bf16_t*)(ws + WS_Z), (const bf16_t*)(ws + WS_W + (size_t)l * LW + OW_2), FF, FF, 0, 0, nullptr, nullptr}; pg8::StaticOrder S; S.init(M, D, G, vcu, true); S.revr = true;
;             EpiFinal E{(const bf16_t*)(ws + WS_H), ap->out, (float*)(ws + WS_SSP) + (size_t)4 * M * 8, ap->in[18], (LAS float*)(lds + 131072 + 1024), xbar, xlocal};
;             pg8::gemm_phase<EpiFinal>(lds, g, S, E, wave_s);
.LBB0_864:
	v_readlane_b32 s4, v254, 53
	v_readlane_b32 s5, v254, 54
	s_mov_b64 s[2:3], -1
	s_and_b64 vcc, exec, s[4:5]
	s_cbranch_vccz .LBB0_986
	s_mov_b64 s[100:101], 0x800
	s_mov_b64 s[2:3], s[66:67]
	v_mbcnt_lo_u32_b32 v0, -1, 0
	v_mbcnt_hi_u32_b32 v0, -1, v0
	s_and_b64 vcc, exec, s[22:23]
	v_add_u32_e32 v16, s81, v0
	s_nop 0
	v_readfirstlane_b32 s10, v16
	s_cbranch_vccnz .LBB0_869
	v_readlane_b32 s4, v254, 40
	v_readlane_b32 s5, v254, 41
	s_andn2_b64 vcc, exec, s[4:5]
	v_readlane_b32 s4, v254, 44
	s_cbranch_vccnz .LBB0_868
	v_readlane_b32 s4, v254, 42

; #define PG8_STAGE(bufoff, gbase, voff) do { _Pragma("unroll") for (int _i = 0; _i < 2; ++_i) \
;         __builtin_amdgcn_global_load_lds((const unsigned*)((const char*)(gbase) + (voff)[_i]), (LAS unsigned*)(lds + (bufoff) + ldsw + _i * 8192), 16, 0, 0); } while (0)
; #define PG8_BAR __builtin_amdgcn_s_barrier()
;     ...
;     const int wid = __builtin_amdgcn_readfirstlane(tid >> 6), lane = tid & 63, wr = wid >> 2, wc = wid & 3, fr = lane & 15, fq = lane >> 4;
;     const int K = g.K, nt = K / BK, lda = g.lda;
;     unsigned voffA[2], voffB[2];
; #pragma unroll
;     for (int i = 0; i < 2; ++i) { int R, C; stage_rc(tid * 16 + i * 8192, R, C); const int Rb = Epi::PERM ? ((R & ~31) + perm32(R & 31)) : R;
;         voffA[i] = (unsigned)(R * lda + C) * 2u; voffB[i] = (unsigned)(Rb * K + C) * 2u; }
;     const size_t kstep = (size_t)(BK * 2);
;     const size_t hstepA = (size_t)HALF * lda * 2, hstepB = (size_t)HALF * K * 2;
;     const size_t tstepA = 2 * hstepA, tstepB = 2 * hstepB;
;     const unsigned ldsw = (unsigned)wid * 1024u;
;     const int aoff = lds_byte(wr * 64 + fr, fq * 8), boff = lds_byte(wc * 32 + fr, fq * 8);
;     ...
;     Unit cur, nxt; int ui = 0;
;     if (!S.next(0, cur)) return;
;     f32x4 acc[2][2][4][2];
; #pragma unroll
;     for (int a = 0; a < 2; ++a)
; #pragma unroll
;         for (int b = 0; b < 2; ++b)
; #pragma unroll
;             for (int m = 0; m < 4; ++m)
; #pragma unroll
;                 for (int n = 0; n < 2; ++n) acc[a][b][m][n] = (f32x4){0.f, 0.f, 0.f, 0.f};
;     bf16x8 At[4][2], B0[2][2], B1[2][2];
;     const char* cA = (const char*)g.A + (size_t)cur.pm * tstepA + (size_t)((cur.pn >> g.ash) * g.amul) * 2; const char* cB = (const char*)g.Bt + (size_t)cur.pn * tstepB;
;     PG8_STAGE(PG8_SB(0, 0), cB, voffB); PG8_STAGE(PG8_SB(0, 1), cB + hstepB, voffB); PG8_STAGE(PG8_SA(0, 0), cA, voffA); PG8_STAGE(PG8_SA(0, 1), cA + hstepA, voffA);
;     if (wr == 1) PG8_BAR;
.LBB0_869:
	s_load_dwordx4 s[48:51], s[2:3], 0x90
	s_load_dwordx2 s[6:7], s[2:3], 0xa0
	s_and_b64 vcc, exec, s[22:23]
	s_cbranch_vccnz .LBB0_985
	v_ashrrev_i32_e32 v0, 31, v16
	v_lshrrev_b32_e32 v0, 26, v0
	v_add_u32_e32 v0, v16, v0
	v_ashrrev_i32_e32 v10, 6, v0
	v_bfe_i32 v0, v16, 27, 1
	v_lshlrev_b32_e32 v2, 4, v16
	v_lshrrev_b32_e32 v0, 22, v0
	v_add_u32_e32 v0, v2, v0
	v_and_b32_e32 v0, 0xfffffc00, v0
	v_sub_u32_e32 v0, v2, v0
	v_lshrrev_b32_e32 v3, 4, v0
	v_bitop3_b32 v0, v3, v0, 32 bitop3:0x6c
	v_ashrrev_i32_e32 v4, 31, v0
	v_lshrrev_b32_e32 v4, 26, v4
	s_waitcnt lgkmcnt(0)
	s_add_u32 s25, s6, 0x12800000
	v_add_u32_e32 v4, v0, v4
	s_addc_u32 s28, s7, 0
	v_readlane_b32 s2, v254, 55
	v_lshlrev_b32_e32 v3, 3, v10
	v_ashrrev_i32_e32 v11, 6, v4
	v_and_b32_e32 v4, 0xc0, v4
	s_add_u32 s2, s6, s2
	v_and_b32_e32 v3, -16, v3
	v_sub_u32_e32 v0, v0, v4
	s_addc_u32 s3, s7, 0
	v_add_u32_e32 v3, v11, v3
	v_ashrrev_i16_sdwa v0, v227, sext(v0) dst_sel:DWORD dst_unused:UNUSED_PAD src0_sel:DWORD src1_sel:BYTE_0
	s_add_u32 s29, s2, 0x7400000
	v_lshlrev_b32_e32 v5, 5, v10
	v_bfe_i32 v12, v0, 0, 16
	v_lshlrev_b32_e32 v0, 1, v3
	v_lshrrev_b32_e32 v4, 2, v3
	v_and_b32_e32 v6, 3, v11
	s_mov_b32 s2, 0x3ffe0
	v_and_b32_e32 v5, 32, v5
	v_and_b32_e32 v0, 24, v0
	v_and_b32_e32 v4, 4, v4
	v_and_or_b32 v6, v3, s2, v6
	v_or3_b32 v0, v6, v4, v0
	v_add_lshl_u32 v4, v5, v12, 1
	v_add_u32_e32 v2, 0x2000, v2
	v_lshl_add_u32 v158, v3, 14, v4
	v_lshrrev_b32_e32 v255, 14, v158
	v_and_b32_e32 v250, 0x3fff, v158
	v_and_b32_e32 v158, 0xfffffff0, v255
	v_lshlrev_b32_e32 v158, 14, v158
	v_and_b32_e32 v255, 15, v255
	v_lshl_add_u32 v158, v255, 6, v158
	v_and_b32_e32 v255, 64, v250
	v_lshl_add_u32 v158, v255, 4, v158
	v_and_b32_e32 v250, 63, v250
	v_add_u32_e32 v158, v158, v250
	v_ashrrev_i32_e32 v3, 31, v2
	v_lshrrev_b32_e32 v3, 22, v3
	v_add_u32_e32 v3, v2, v3
	v_ashrrev_i32_e32 v13, 10, v3
	v_mul_i32_i24_e32 v3, 0x400, v13
	v_sub_u32_e32 v2, v2, v3
	v_lshrrev_b32_e32 v3, 4, v2
	v_bitop3_b32 v2, v3, v2, 32 bitop3:0x6c
	v_lshl_add_u32 v0, v0, 14, v4
	v_ashrrev_i32_e32 v4, 31, v2
	v_lshrrev_b32_e32 v4, 26, v4
	v_lshlrev_b32_e32 v3, 3, v13
	v_add_u32_e32 v4, v2, v4
	v_and_b32_e32 v3, -16, v3
	v_ashrrev_i32_e32 v14, 6, v4
	s_addc_u32 s56, s3, 0
	s_ashr_i32 s8, s10, 6
	v_add_u32_e32 v3, v14, v3
	v_and_b32_e32 v4, 0xc0, v4
	v_and_b32_e32 v6, 3, v14
	s_ashr_i32 s21, s20, 31
	s_ashr_i32 s19, s18, 31
	v_sub_u32_e32 v2, v2, v4
	v_and_or_b32 v6, v3, s2, v6
	s_ashr_i32 s9, s10, 8
	s_lshl_b32 s57, s8, 10
	s_lshl_b64 s[2:3], s[20:21], 22
	s_lshl_b64 s[4:5], s[18:19], 22
	v_ashrrev_i16_sdwa v2, v227, sext(v2) dst_sel:DWORD dst_unused:UNUSED_PAD src0_sel:DWORD src1_sel:BYTE_0
	s_add_u32 s62, s29, s4
	v_lshlrev_b32_e32 v5, 5, v13
	v_bfe_i32 v15, v2, 0, 16
	v_lshlrev_b32_e32 v2, 1, v3
	v_lshrrev_b32_e32 v4, 2, v3
	s_addc_u32 s63, s56, s5
	s_add_i32 s60, s57, 0
	v_and_b32_e32 v5, 32, v5
	v_and_b32_e32 v2, 24, v2
	v_and_b32_e32 v4, 4, v4
	s_add_i32 m0, s60, 0x10000
	v_or3_b32 v2, v6, v4, v2
	v_add_lshl_u32 v4, v5, v15, 1
	global_load_lds_dwordx4 v0, s[62:63]
	s_add_i32 m0, s60, 0x12000
	v_lshl_add_u32 v162, v2, 14, v4
	s_add_u32 s4, s62, 0x200000
	global_load_lds_dwordx4 v162, s[62:63]
	s_addc_u32 s5, s63, 0
	s_add_i32 m0, s60, 0x14000
	v_lshl_add_u32 v160, v3, 14, v4
	v_lshrrev_b32_e32 v255, 14, v160
	v_and_b32_e32 v250, 0x3fff, v160
	v_and_b32_e32 v160, 0xfffffff0, v255
	v_lshlrev_b32_e32 v160, 14, v160
	v_and_b32_e32 v255, 15, v255
	v_lshl_add_u32 v160, v255, 6, v160
	v_and_b32_e32 v255, 64, v250
	v_lshl_add_u32 v160, v255, 4, v160
	v_and_b32_e32 v250, 63, v250
	v_add_u32_e32 v160, v160, v250
	global_load_lds_dwordx4 v0, s[4:5]
	s_add_i32 m0, s60, 0x16000
	s_add_u32 s46, s25, s2
	s_addc_u32 s47, s28, s3
	s_add_i32 s61, s60, 0x2000
	global_load_lds_dwordx4 v162, s[4:5]
	s_mov_b32 m0, s60
	s_add_u32 s2, s46, 0x200000
	global_load_lds_dwordx4 v158, s[46:47]
	s_mov_b32 m0, s61
	s_addc_u32 s3, s47, 0
	s_add_i32 s76, s60, 0x4000
	global_load_lds_dwordx4 v160, s[46:47]
	s_mov_b32 m0, s76
	s_add_i32 s77, s60, 0x6000
	global_load_lds_dwordx4 v158, s[2:3]
	s_mov_b32 m0, s77
	v_mov_b32_e32 v163, v1
	global_load_lds_dwordx4 v160, s[2:3]
	v_mov_b32_e32 v159, v1
	v_mov_b32_e32 v161, v1
	s_cmp_eq_u32 s9, 1
	v_lshl_add_u64 v[8:9], s[62:63], 0, v[0:1]
	v_lshl_add_u64 v[6:7], s[62:63], 0, v[162:163]
	v_lshl_add_u64 v[2:3], s[46:47], 0, v[158:159]
	s_cselect_b64 s[2:3], -1, 0
	s_cmp_lg_u32 s9, 1
	v_lshl_add_u64 v[4:5], s[46:47], 0, v[160:161]
	s_cbranch_scc1 .LBB0_872
	s_barrier
; #define PG8_STAGE(bufoff, gbase, voff) do { _Pragma("unroll") for (int _i = 0; _i < 2; ++_i) \
;         __builtin_amdgcn_global_load_lds((const unsigned*)((const char*)(gbase) + (voff)[_i]), (LAS unsigned*)(lds + (bufoff) + ldsw + _i * 8192), 16, 0, 0); } while (0)
; #define PG8_WAIT_V(n) asm volatile("s_waitcnt vmcnt(" #n ")" ::: "memory")
; #define PG8_BAR __builtin_amdgcn_s_barrier()
;     ...
;     if (wr == 1) PG8_BAR;
;     PG8_WAIT_V(2); PG8_BAR;
;     PG8_STAGE(PG8_SB(1, 0), cB + kstep, voffB); PG8_STAGE(PG8_SA(1, 0), cA + kstep, voffA); PG8_STAGE(PG8_SB(1, 1), cB + hstepB + kstep, voffB);
;     PG8_WAIT_V(6); PG8_BAR;
.LBB0_872:
	s_add_u32 s4, s6, 0x2e800000
	s_addc_u32 s5, s7, 0
	v_bfe_u32 v18, v16, 4, 2
	s_add_u32 s6, s6, 0x36e00000
	v_and_b32_e32 v17, 15, v16
	v_lshlrev_b32_e32 v20, 4, v18
	v_lshlrev_b32_e32 v16, 2, v16
	s_addc_u32 s7, s7, 0
	s_and_b32 s12, s8, 3
	v_lshl_or_b32 v21, v17, 6, v20
	s_lshl_b32 s8, s9, 13
	v_and_b32_e32 v16, 32, v16
	s_add_i32 m0, s60, 0x18000
	v_lshl_add_u64 v[8:9], v[8:9], 0, s[34:35]
	v_bitop3_b32 v22, v21, s8, v16 bitop3:0xde
	s_lshl_b32 s8, s12, 12
	s_waitcnt vmcnt(2)
	s_barrier
	global_load_lds_dwordx4 v[8:9], off
	v_lshl_add_u64 v[6:7], v[6:7], 0, s[34:35]
	s_add_i32 m0, s60, 0x1a000
	s_add_i32 s81, s60, 0x8000
	s_add_i32 s82, s60, 0xa000
	v_bitop3_b32 v209, v21, s8, v16 bitop3:0xde
	global_load_lds_dwordx4 v[6:7], off
	v_lshl_add_u64 v[2:3], v[2:3], 0, s[100:101]
	s_mov_b32 m0, s81
	s_add_u32 s8, s62, 0x200080
	v_lshl_or_b32 v207, s9, 6, v17
	global_load_lds_dwordx4 v[2:3], off
	v_lshl_add_u64 v[2:3], v[4:5], 0, s[100:101]
	s_mov_b32 m0, s82
	s_addc_u32 s9, s63, 0
	global_load_lds_dwordx4 v[2:3], off
	s_add_i32 m0, s60, 0x1c000
	v_lshl_add_u64 v[2:3], s[8:9], 0, v[0:1]
	global_load_lds_dwordx4 v[2:3], off
	v_lshl_add_u64 v[2:3], s[8:9], 0, v[162:163]
	s_add_i32 m0, s60, 0x1e000
	s_cmpk_lt_u32 s10, 0x100
	global_load_lds_dwordx4 v[2:3], off
	s_cselect_b64 s[8:9], -1, 0
	s_and_b32 s10, s10, 0xffffff00
	s_lshl_b32 s13, s12, 6
	s_or_b32 s10, s13, s10
	v_or3_b32 v213, s10, v20, v17
	s_movk_i32 s10, 0x100
	v_cmp_gt_i32_e64 s[42:43], s10, v213
	s_lshl_b32 s10, s12, 2
	v_lshlrev_b32_e32 v19, 3, v18
	s_add_i32 s10, s10, 0
	v_lshl_or_b32 v211, s12, 5, v19
	v_lshlrev_b32_e32 v2, 4, v207
	s_add_i32 s12, s10, 0x20400
	v_add_u32_e32 v216, s12, v2
	s_add_i32 s12, s10, 0x20500
	v_add_u32_e32 v217, s12, v2
	s_add_i32 s12, s10, 0x20600
	v_add_u32_e32 v218, s12, v2
	s_add_i32 s12, s10, 0x20700
	v_add_u32_e32 v219, s12, v2
	s_add_i32 s12, s10, 0x20c00
	v_add_u32_e32 v220, s12, v2
	s_add_i32 s12, s10, 0x20d00
	v_add_u32_e32 v221, s12, v2
	s_add_i32 s12, s10, 0x20e00
	s_add_i32 s10, s10, 0x20f00
	v_add_u32_e32 v222, s12, v2
	v_add_u32_e32 v223, s10, v2
	v_lshlrev_b32_e32 v2, 17, v10
	v_and_b32_e32 v2, 0xfffc0000, v2
	v_lshl_add_u32 v2, v11, 14, v2
	v_and_b32_e32 v4, 1, v10
	v_lshl_or_b32 v2, v4, 6, v2
	v_lshl_add_u32 v164, v12, 1, v2
	v_lshrrev_b32_e32 v255, 14, v164
	v_and_b32_e32 v250, 0x3fff, v164
	v_and_b32_e32 v164, 0xfffffff0, v255
	v_lshlrev_b32_e32 v164, 14, v164
	v_and_b32_e32 v255, 15, v255
	v_lshl_add_u32 v164, v255, 6, v164
	v_and_b32_e32 v255, 64, v250
	v_lshl_add_u32 v164, v255, 4, v164
	v_and_b32_e32 v250, 63, v250
	v_add_u32_e32 v164, v164, v250
	v_lshlrev_b32_e32 v2, 17, v13
	v_and_b32_e32 v2, 0xfffc0000, v2
	v_lshl_add_u32 v2, v14, 14, v2
	v_and_b32_e32 v4, 1, v13
	s_waitcnt vmcnt(6)
	v_lshlrev_b32_e32 v3, 4, v213
	v_lshl_or_b32 v2, v4, 6, v2
	v_lshl_add_u32 v166, v15, 1, v2
	v_lshrrev_b32_e32 v255, 14, v166
	v_and_b32_e32 v250, 0x3fff, v166
	v_and_b32_e32 v166, 0xfffffff0, v255
	v_lshlrev_b32_e32 v166, 14, v166
	v_and_b32_e32 v255, 15, v255
	v_lshl_add_u32 v166, v255, 6, v166
	v_and_b32_e32 v255, 64, v250
	v_lshl_add_u32 v166, v255, 4, v166
	v_and_b32_e32 v250, 63, v250
	v_add_u32_e32 v166, v166, v250
	v_add_u32_e32 v2, 0, v3
	v_readlane_b32 s66, v253, 1
	s_mov_b32 s11, 0
	v_cmp_eq_u32_e64 s[40:41], 0, v18
	v_mov_b32_e32 v165, v1
	v_mov_b32_e32 v167, v1
	v_add_u32_e32 v224, 0, v22
	v_add_u32_e32 v225, 0x20400, v2
	v_readlane_b32 s67, v253, 2
	s_barrier
	s_branch .LBB0_875

; #define PG8_BAR __builtin_amdgcn_s_barrier()
;     ...
;         const bool has_next = S.next(ui + 1, nxt);
;         const char* nA = has_next ? (const char*)g.A + (size_t)nxt.pm * tstepA + (size_t)((nxt.pn >> g.ash) * g.amul) * 2 : cA; const char* nB = has_next ? (const char*)g.Bt + (size_t)nxt.pn * tstepB : cB;
;         PG8_KLOOP();
;         if (wr == 0) PG8_BAR;
;         E(acc, cur, wr, wc, fr, fq);
;         if (!has_next) break;
; #pragma unroll
;         for (int a = 0; a < 2; ++a)
; #pragma unroll
;             for (int b = 0; b < 2; ++b)
; #pragma unroll
;                 for (int m = 0; m < 4; ++m)
; #pragma unroll
;                     for (int n = 0; n < 2; ++n) acc[a][b][m][n] = (f32x4){0.f, 0.f, 0.f, 0.f};
;         cur = nxt; cA = nA; cB = nB; ++ui;
.LBB0_881:
	s_ashr_i32 s13, s12, 31
	s_lshl_b64 s[14:15], s[12:13], 22
	s_add_u32 s14, s25, s14
	s_addc_u32 s15, s28, s15
	s_and_b64 s[16:17], s[44:45], exec
	s_cselect_b32 s13, s15, s47
	s_cselect_b32 s19, s14, s46
	s_ashr_i32 s11, s10, 31
	s_lshl_b64 s[16:17], s[10:11], 22
	s_add_u32 s16, s29, s16
	s_addc_u32 s17, s56, s17
	s_and_b64 s[22:23], s[44:45], exec
	s_cselect_b32 s11, s17, s63
	s_cselect_b32 s21, s16, s62
	s_add_u32 s46, s46, 0x200800
	s_addc_u32 s47, s47, 0
	s_add_u32 s36, s62, 0x100
	v_mov_b32_e32 v2, 0
	s_addc_u32 s37, s63, 0
	s_mov_b32 s39, -2
	v_mov_b32_e32 v3, v2
	v_mov_b32_e32 v4, v2
	v_mov_b32_e32 v5, v2
	v_mov_b32_e32 v6, v2
	v_mov_b32_e32 v7, v2
	v_mov_b32_e32 v8, v2
	v_mov_b32_e32 v9, v2
	v_mov_b32_e32 v18, v2
	v_mov_b32_e32 v19, v2
	v_mov_b32_e32 v20, v2
	v_mov_b32_e32 v21, v2
	v_mov_b32_e32 v22, v2
	v_mov_b32_e32 v23, v2
	v_mov_b32_e32 v24, v2
	v_mov_b32_e32 v25, v2
	v_mov_b32_e32 v34, v2
	v_mov_b32_e32 v35, v2
	v_mov_b32_e32 v36, v2
	v_mov_b32_e32 v37, v2
	v_mov_b32_e32 v38, v2
	v_mov_b32_e32 v39, v2
	v_mov_b32_e32 v40, v2
	v_mov_b32_e32 v41, v2
	v_mov_b32_e32 v50, v2
	v_mov_b32_e32 v51, v2
	v_mov_b32_e32 v52, v2
	v_mov_b32_e32 v53, v2
	v_mov_b32_e32 v54, v2
	v_mov_b32_e32 v55, v2
	v_mov_b32_e32 v56, v2
	v_mov_b32_e32 v57, v2
	v_mov_b32_e32 v10, v2
	v_mov_b32_e32 v11, v2
	v_mov_b32_e32 v12, v2
	v_mov_b32_e32 v13, v2
	v_mov_b32_e32 v14, v2
	v_mov_b32_e32 v15, v2
	v_mov_b32_e32 v16, v2
	v_mov_b32_e32 v17, v2
	v_mov_b32_e32 v26, v2
	v_mov_b32_e32 v27, v2
	v_mov_b32_e32 v28, v2
	v_mov_b32_e32 v29, v2
	v_mov_b32_e32 v30, v2
	v_mov_b32_e32 v31, v2
	v_mov_b32_e32 v32, v2
	v_mov_b32_e32 v33, v2
	v_mov_b32_e32 v42, v2
	v_mov_b32_e32 v43, v2
	v_mov_b32_e32 v44, v2
	v_mov_b32_e32 v45, v2
	v_mov_b32_e32 v46, v2
	v_mov_b32_e32 v47, v2
	v_mov_b32_e32 v48, v2
	v_mov_b32_e32 v49, v2
	v_mov_b32_e32 v58, v2
	v_mov_b32_e32 v59, v2
	v_mov_b32_e32 v60, v2
	v_mov_b32_e32 v61, v2
	v_mov_b32_e32 v62, v2
	v_mov_b32_e32 v63, v2
	v_mov_b32_e32 v64, v2
	v_mov_b32_e32 v65, v2
	v_mov_b32_e32 v66, v2
	v_mov_b32_e32 v67, v2
	v_mov_b32_e32 v68, v2
	v_mov_b32_e32 v69, v2
	v_mov_b32_e32 v70, v2
	v_mov_b32_e32 v71, v2
	v_mov_b32_e32 v72, v2
	v_mov_b32_e32 v73, v2
	v_mov_b32_e32 v82, v2
	v_mov_b32_e32 v83, v2
	v_mov_b32_e32 v84, v2
	v_mov_b32_e32 v85, v2
	v_mov_b32_e32 v86, v2
	v_mov_b32_e32 v87, v2
	v_mov_b32_e32 v88, v2
	v_mov_b32_e32 v89, v2
	v_mov_b32_e32 v98, v2
	v_mov_b32_e32 v99, v2
	v_mov_b32_e32 v100, v2
	v_mov_b32_e32 v101, v2
	v_mov_b32_e32 v102, v2
	v_mov_b32_e32 v103, v2
	v_mov_b32_e32 v104, v2
	v_mov_b32_e32 v105, v2
	v_mov_b32_e32 v114, v2
	v_mov_b32_e32 v115, v2
	v_mov_b32_e32 v116, v2
	v_mov_b32_e32 v117, v2
	v_mov_b32_e32 v118, v2
	v_mov_b32_e32 v119, v2
	v_mov_b32_e32 v120, v2
	v_mov_b32_e32 v121, v2
	v_mov_b32_e32 v74, v2
	v_mov_b32_e32 v75, v2
	v_mov_b32_e32 v76, v2
	v_mov_b32_e32 v77, v2
	v_mov_b32_e32 v78, v2
	v_mov_b32_e32 v79, v2
	v_mov_b32_e32 v80, v2
	v_mov_b32_e32 v81, v2
	v_mov_b32_e32 v90, v2
	v_mov_b32_e32 v91, v2
	v_mov_b32_e32 v92, v2
	v_mov_b32_e32 v93, v2
	v_mov_b32_e32 v94, v2
	v_mov_b32_e32 v95, v2
	v_mov_b32_e32 v96, v2
	v_mov_b32_e32 v97, v2
	v_mov_b32_e32 v106, v2
	v_mov_b32_e32 v107, v2
	v_mov_b32_e32 v108, v2
	v_mov_b32_e32 v109, v2
	v_mov_b32_e32 v110, v2
	v_mov_b32_e32 v111, v2
	v_mov_b32_e32 v112, v2
	v_mov_b32_e32 v113, v2
	v_mov_b32_e32 v122, v2
	v_mov_b32_e32 v123, v2
	v_mov_b32_e32 v124, v2
	v_mov_b32_e32 v125, v2
	v_mov_b32_e32 v126, v2
	v_mov_b32_e32 v127, v2
	v_mov_b32_e32 v128, v2
	v_mov_b32_e32 v129, v2
.LBB0_882:
	s_add_u32 s22, s46, 0xffe00800
	s_addc_u32 s23, s47, -1
	s_add_i32 s24, 0, 0x10000
	s_cmpk_eq_i32 s39, 0x7c
	s_cselect_b32 s23, s13, s23
	s_cselect_b32 s22, s19, s22
	s_cselect_b32 s27, s11, s37
	s_cselect_b32 s26, s21, s36
	s_add_i32 s64, 0, 0x14000
	v_add_u32_e32 v142, s24, v209
	v_add_u32_e32 v168, s64, v209
	ds_read_b128 v[130:133], v142
	ds_read_b128 v[134:137], v142 offset:1024
	ds_read_b128 v[138:141], v142 offset:2048
	ds_read_b128 v[142:145], v142 offset:3072
	ds_read_b128 v[146:149], v168
	ds_read_b128 v[150:153], v168 offset:1024
	ds_read_b128 v[154:157], v168 offset:2048
	ds_read_b128 v[168:171], v168 offset:3072
	v_lshl_add_u64 v[204:205], s[46:47], 0, v[164:165]
	s_add_i32 m0, s60, 0xc000
	ds_read_b128 v[172:175], v224
	ds_read_b128 v[176:179], v224 offset:1024
	ds_read_b128 v[180:183], v224 offset:2048
	ds_read_b128 v[184:187], v224 offset:3072
	ds_read_b128 v[188:191], v224 offset:4096
	ds_read_b128 v[192:195], v224 offset:5120
	ds_read_b128 v[196:199], v224 offset:6144
	ds_read_b128 v[200:203], v224 offset:7168
	global_load_lds_dwordx4 v[204:205], off
	v_lshl_add_u64 v[204:205], s[46:47], 0, v[166:167]
	s_add_i32 m0, s60, 0xe000
	s_nop 0
	global_load_lds_dwordx4 v[204:205], off
	s_waitcnt vmcnt(8)
	s_waitcnt lgkmcnt(0)
	s_setprio 1
	s_barrier
	v_mfma_f32_16x16x32_bf16 v[126:129], v[130:133], v[172:175], v[126:129]
	v_mfma_f32_16x16x32_bf16 v[122:125], v[138:141], v[172:175], v[122:125]
	v_mfma_f32_16x16x32_bf16 v[110:113], v[130:133], v[180:183], v[110:113]
	v_mfma_f32_16x16x32_bf16 v[106:109], v[138:141], v[180:183], v[106:109]
	v_mfma_f32_16x16x32_bf16 v[94:97], v[130:133], v[188:191], v[94:97]
	v_mfma_f32_16x16x32_bf16 v[90:93], v[138:141], v[188:191], v[90:93]
	v_mfma_f32_16x16x32_bf16 v[78:81], v[130:133], v[196:199], v[78:81]
	v_mfma_f32_16x16x32_bf16 v[74:77], v[138:141], v[196:199], v[74:77]
	v_mfma_f32_16x16x32_bf16 v[126:129], v[134:137], v[176:179], v[126:129]
	v_mfma_f32_16x16x32_bf16 v[122:125], v[142:145], v[176:179], v[122:125]
	v_mfma_f32_16x16x32_bf16 v[110:113], v[134:137], v[184:187], v[110:113]
	v_mfma_f32_16x16x32_bf16 v[106:109], v[142:145], v[184:187], v[106:109]
	v_mfma_f32_16x16x32_bf16 v[94:97], v[134:137], v[192:195], v[94:97]
	v_mfma_f32_16x16x32_bf16 v[90:93], v[142:145], v[192:195], v[90:93]
	v_mfma_f32_16x16x32_bf16 v[78:81], v[134:137], v[200:203], v[78:81]
	v_mfma_f32_16x16x32_bf16 v[74:77], v[142:145], v[200:203], v[74:77]
	s_setprio 0
	s_setprio 1
	v_mfma_f32_16x16x32_bf16 v[118:121], v[146:149], v[172:175], v[118:121]
	v_mfma_f32_16x16x32_bf16 v[114:117], v[154:157], v[172:175], v[114:117]
	v_mfma_f32_16x16x32_bf16 v[102:105], v[146:149], v[180:183], v[102:105]
	v_mfma_f32_16x16x32_bf16 v[98:101], v[154:157], v[180:183], v[98:101]
	v_mfma_f32_16x16x32_bf16 v[86:89], v[146:149], v[188:191], v[86:89]
	v_mfma_f32_16x16x32_bf16 v[82:85], v[154:157], v[188:191], v[82:85]
	v_mfma_f32_16x16x32_bf16 v[70:73], v[146:149], v[196:199], v[70:73]
	v_mfma_f32_16x16x32_bf16 v[66:69], v[154:157], v[196:199], v[66:69]
	v_mfma_f32_16x16x32_bf16 v[118:121], v[150:153], v[176:179], v[118:121]
	v_mfma_f32_16x16x32_bf16 v[114:117], v[168:171], v[176:179], v[114:117]
	v_mfma_f32_16x16x32_bf16 v[102:105], v[150:153], v[184:187], v[102:105]
	v_mfma_f32_16x16x32_bf16 v[98:101], v[168:171], v[184:187], v[98:101]
	v_mfma_f32_16x16x32_bf16 v[86:89], v[150:153], v[192:195], v[86:89]
	v_mfma_f32_16x16x32_bf16 v[82:85], v[168:171], v[192:195], v[82:85]
	v_mfma_f32_16x16x32_bf16 v[70:73], v[150:153], v[200:203], v[70:73]
	v_mfma_f32_16x16x32_bf16 v[66:69], v[168:171], v[200:203], v[66:69]
	s_barrier
	s_setprio 0
	s_add_i32 s24, s24, s57
	v_lshl_add_u64 v[204:205], s[26:27], 0, v[0:1]
	s_mov_b32 m0, s24
	ds_read_b128 v[172:175], v224 offset:16384
	ds_read_b128 v[176:179], v224 offset:17408
	ds_read_b128 v[180:183], v224 offset:18432
	ds_read_b128 v[184:187], v224 offset:19456
	ds_read_b128 v[188:191], v224 offset:20480
	ds_read_b128 v[192:195], v224 offset:21504
	ds_read_b128 v[196:199], v224 offset:22528
	ds_read_b128 v[200:203], v224 offset:23552
	global_load_lds_dwordx4 v[204:205], off
	s_add_i32 m0, s24, 0x2000
	s_add_u32 s62, s26, 0x200000
	v_lshl_add_u64 v[214:215], s[26:27], 0, v[162:163]
	s_addc_u32 s63, s27, 0
	s_add_i32 s24, s64, s57
	global_load_lds_dwordx4 v[214:215], off
	v_lshl_add_u64 v[230:231], s[62:63], 0, v[0:1]
	s_mov_b32 m0, s24
	v_lshl_add_u64 v[232:233], s[22:23], 0, v[160:161]
	global_load_lds_dwordx4 v[230:231], off
	v_lshl_add_u64 v[230:231], s[62:63], 0, v[162:163]
	s_add_i32 m0, s24, 0x2000
	s_nop 0
	global_load_lds_dwordx4 v[230:231], off
	v_lshl_add_u64 v[230:231], s[22:23], 0, v[158:159]
	s_mov_b32 m0, s60
	s_nop 0
	global_load_lds_dwordx4 v[230:231], off
	s_mov_b32 m0, s61
	s_nop 0
	global_load_lds_dwordx4 v[232:233], off
	s_waitcnt vmcnt(8)
	s_waitcnt lgkmcnt(0)
	s_setprio 1
	s_barrier
	v_mfma_f32_16x16x32_bf16 v[62:65], v[130:133], v[172:175], v[62:65]
	v_mfma_f32_16x16x32_bf16 v[58:61], v[138:141], v[172:175], v[58:61]
	v_mfma_f32_16x16x32_bf16 v[46:49], v[130:133], v[180:183], v[46:49]
	v_mfma_f32_16x16x32_bf16 v[42:45], v[138:141], v[180:183], v[42:45]
	v_mfma_f32_16x16x32_bf16 v[30:33], v[130:133], v[188:191], v[30:33]
	v_mfma_f32_16x16x32_bf16 v[26:29], v[138:141], v[188:191], v[26:29]
	v_mfma_f32_16x16x32_bf16 v[14:17], v[130:133], v[196:199], v[14:17]
	v_mfma_f32_16x16x32_bf16 v[10:13], v[138:141], v[196:199], v[10:13]
	v_mfma_f32_16x16x32_bf16 v[62:65], v[134:137], v[176:179], v[62:65]
	v_mfma_f32_16x16x32_bf16 v[58:61], v[142:145], v[176:179], v[58:61]
	v_mfma_f32_16x16x32_bf16 v[46:49], v[134:137], v[184:187], v[46:49]
	v_mfma_f32_16x16x32_bf16 v[42:45], v[142:145], v[184:187], v[42:45]
	v_mfma_f32_16x16x32_bf16 v[30:33], v[134:137], v[192:195], v[30:33]
	v_mfma_f32_16x16x32_bf16 v[26:29], v[142:145], v[192:195], v[26:29]
	v_mfma_f32_16x16x32_bf16 v[14:17], v[134:137], v[200:203], v[14:17]
	v_mfma_f32_16x16x32_bf16 v[10:13], v[142:145], v[200:203], v[10:13]
	s_setprio 0
	s_setprio 1
	v_mfma_f32_16x16x32_bf16 v[54:57], v[146:149], v[172:175], v[54:57]
	v_mfma_f32_16x16x32_bf16 v[50:53], v[154:157], v[172:175], v[50:53]
	v_mfma_f32_16x16x32_bf16 v[38:41], v[146:149], v[180:183], v[38:41]
	v_mfma_f32_16x16x32_bf16 v[34:37], v[154:157], v[180:183], v[34:37]
	v_mfma_f32_16x16x32_bf16 v[22:25], v[146:149], v[188:191], v[22:25]
	v_mfma_f32_16x16x32_bf16 v[18:21], v[154:157], v[188:191], v[18:21]
	v_mfma_f32_16x16x32_bf16 v[6:9], v[146:149], v[196:199], v[6:9]
	v_mfma_f32_16x16x32_bf16 v[2:5], v[154:157], v[196:199], v[2:5]
	v_mfma_f32_16x16x32_bf16 v[54:57], v[150:153], v[176:179], v[54:57]
	v_mfma_f32_16x16x32_bf16 v[50:53], v[168:171], v[176:179], v[50:53]
	v_mfma_f32_16x16x32_bf16 v[38:41], v[150:153], v[184:187], v[38:41]
	v_mfma_f32_16x16x32_bf16 v[34:37], v[168:171], v[184:187], v[34:37]
	v_mfma_f32_16x16x32_bf16 v[22:25], v[150:153], v[192:195], v[22:25]
	v_mfma_f32_16x16x32_bf16 v[18:21], v[168:171], v[192:195], v[18:21]
	v_mfma_f32_16x16x32_bf16 v[6:9], v[150:153], v[200:203], v[6:9]
	v_mfma_f32_16x16x32_bf16 v[2:5], v[168:171], v[200:203], v[2:5]
	s_barrier
	s_setprio 0
	s_add_i32 s24, 0, 0x18000
	s_add_i32 s62, 0, 0x1c000
	v_add_u32_e32 v142, s24, v209
	v_add_u32_e32 v168, s62, v209
	ds_read_b128 v[130:133], v142
	ds_read_b128 v[134:137], v142 offset:1024
	ds_read_b128 v[138:141], v142 offset:2048
	ds_read_b128 v[142:145], v142 offset:3072
	ds_read_b128 v[146:149], v168
	ds_read_b128 v[150:153], v168 offset:1024
	ds_read_b128 v[154:157], v168 offset:2048
	ds_read_b128 v[168:171], v168 offset:3072
	s_add_u32 s22, s22, 0x200000
	s_addc_u32 s23, s23, 0
	s_mov_b32 m0, s76
	v_lshl_add_u64 v[234:235], s[22:23], 0, v[158:159]
	ds_read_b128 v[172:175], v224 offset:32768
	ds_read_b128 v[176:179], v224 offset:33792
	ds_read_b128 v[180:183], v224 offset:34816
	ds_read_b128 v[184:187], v224 offset:35840
	ds_read_b128 v[188:191], v224 offset:36864
	ds_read_b128 v[192:195], v224 offset:37888
	ds_read_b128 v[196:199], v224 offset:38912
	ds_read_b128 v[200:203], v224 offset:39936
	global_load_lds_dwordx4 v[234:235], off
	v_lshl_add_u64 v[234:235], s[22:23], 0, v[160:161]
	s_mov_b32 m0, s77
	s_nop 0
	global_load_lds_dwordx4 v[234:235], off
	s_waitcnt vmcnt(8)
	s_waitcnt lgkmcnt(0)
	s_setprio 1
	s_barrier
	v_mfma_f32_16x16x32_bf16 v[126:129], v[130:133], v[172:175], v[126:129]
	v_mfma_f32_16x16x32_bf16 v[122:125], v[138:141], v[172:175], v[122:125]
	v_mfma_f32_16x16x32_bf16 v[110:113], v[130:133], v[180:183], v[110:113]
	v_mfma_f32_16x16x32_bf16 v[106:109], v[138:141], v[180:183], v[106:109]
	v_mfma_f32_16x16x32_bf16 v[94:97], v[130:133], v[188:191], v[94:97]
	v_mfma_f32_16x16x32_bf16 v[90:93], v[138:141], v[188:191], v[90:93]
	v_mfma_f32_16x16x32_bf16 v[78:81], v[130:133], v[196:199], v[78:81]
	v_mfma_f32_16x16x32_bf16 v[74:77], v[138:141], v[196:199], v[74:77]
	v_mfma_f32_16x16x32_bf16 v[126:129], v[134:137], v[176:179], v[126:129]
	v_mfma_f32_16x16x32_bf16 v[122:125], v[142:145], v[176:179], v[122:125]
	v_mfma_f32_16x16x32_bf16 v[110:113], v[134:137], v[184:187], v[110:113]
	v_mfma_f32_16x16x32_bf16 v[106:109], v[142:145], v[184:187], v[106:109]
	v_mfma_f32_16x16x32_bf16 v[94:97], v[134:137], v[192:195], v[94:97]
	v_mfma_f32_16x16x32_bf16 v[90:93], v[142:145], v[192:195], v[90:93]
	v_mfma_f32_16x16x32_bf16 v[78:81], v[134:137], v[200:203], v[78:81]
	v_mfma_f32_16x16x32_bf16 v[74:77], v[142:145], v[200:203], v[74:77]
	s_setprio 0
	s_setprio 1
	v_mfma_f32_16x16x32_bf16 v[118:121], v[146:149], v[172:175], v[118:121]
	v_mfma_f32_16x16x32_bf16 v[114:117], v[154:157], v[172:175], v[114:117]
	v_mfma_f32_16x16x32_bf16 v[102:105], v[146:149], v[180:183], v[102:105]
	v_mfma_f32_16x16x32_bf16 v[98:101], v[154:157], v[180:183], v[98:101]
	v_mfma_f32_16x16x32_bf16 v[86:89], v[146:149], v[188:191], v[86:89]
	v_mfma_f32_16x16x32_bf16 v[82:85], v[154:157], v[188:191], v[82:85]
	v_mfma_f32_16x16x32_bf16 v[70:73], v[146:149], v[196:199], v[70:73]
	v_mfma_f32_16x16x32_bf16 v[66:69], v[154:157], v[196:199], v[66:69]
	v_mfma_f32_16x16x32_bf16 v[118:121], v[150:153], v[176:179], v[118:121]
	v_mfma_f32_16x16x32_bf16 v[114:117], v[168:171], v[176:179], v[114:117]
	v_mfma_f32_16x16x32_bf16 v[102:105], v[150:153], v[184:187], v[102:105]
	v_mfma_f32_16x16x32_bf16 v[98:101], v[168:171], v[184:187], v[98:101]
	v_mfma_f32_16x16x32_bf16 v[86:89], v[150:153], v[192:195], v[86:89]
	v_mfma_f32_16x16x32_bf16 v[82:85], v[168:171], v[192:195], v[82:85]
	v_mfma_f32_16x16x32_bf16 v[70:73], v[150:153], v[200:203], v[70:73]
	v_mfma_f32_16x16x32_bf16 v[66:69], v[168:171], v[200:203], v[66:69]
	s_barrier
	s_setprio 0
	s_add_i32 s22, s24, s57
	v_lshl_add_u64 v[204:205], v[204:205], 0, s[34:35]
	s_mov_b32 m0, s22
	ds_read_b128 v[172:175], v224 offset:49152
	ds_read_b128 v[176:179], v224 offset:50176
	ds_read_b128 v[180:183], v224 offset:51200
	ds_read_b128 v[184:187], v224 offset:52224
	ds_read_b128 v[188:191], v224 offset:53248
	ds_read_b128 v[192:195], v224 offset:54272
	ds_read_b128 v[196:199], v224 offset:55296
	ds_read_b128 v[200:203], v224 offset:56320
	global_load_lds_dwordx4 v[204:205], off
	s_add_i32 m0, s22, 0x2000
	s_add_u32 s22, s26, 0x200080
	v_lshl_add_u64 v[204:205], v[214:215], 0, s[34:35]
	s_addc_u32 s23, s27, 0
	s_add_i32 s24, s62, s57
	global_load_lds_dwordx4 v[204:205], off
	v_lshl_add_u64 v[204:205], s[22:23], 0, v[0:1]
	s_mov_b32 m0, s24
	s_nop 0
	global_load_lds_dwordx4 v[204:205], off
	v_lshl_add_u64 v[204:205], s[22:23], 0, v[162:163]
	s_add_i32 m0, s24, 0x2000
	s_nop 0
	global_load_lds_dwordx4 v[204:205], off
	v_lshl_add_u64 v[204:205], v[230:231], 0, s[100:101]
	s_mov_b32 m0, s81
	s_nop 0
	global_load_lds_dwordx4 v[204:205], off
	v_lshl_add_u64 v[204:205], v[232:233], 0, s[100:101]
	s_mov_b32 m0, s82
	s_nop 0
	global_load_lds_dwordx4 v[204:205], off
	s_waitcnt vmcnt(8)
	s_waitcnt lgkmcnt(0)
	s_setprio 1
	s_barrier
	v_mfma_f32_16x16x32_bf16 v[62:65], v[130:133], v[172:175], v[62:65]
	v_mfma_f32_16x16x32_bf16 v[58:61], v[138:141], v[172:175], v[58:61]
	v_mfma_f32_16x16x32_bf16 v[46:49], v[130:133], v[180:183], v[46:49]
	v_mfma_f32_16x16x32_bf16 v[42:45], v[138:141], v[180:183], v[42:45]
	v_mfma_f32_16x16x32_bf16 v[30:33], v[130:133], v[188:191], v[30:33]
	v_mfma_f32_16x16x32_bf16 v[26:29], v[138:141], v[188:191], v[26:29]
	v_mfma_f32_16x16x32_bf16 v[14:17], v[130:133], v[196:199], v[14:17]
	v_mfma_f32_16x16x32_bf16 v[10:13], v[138:141], v[196:199], v[10:13]
	v_mfma_f32_16x16x32_bf16 v[62:65], v[134:137], v[176:179], v[62:65]
	v_mfma_f32_16x16x32_bf16 v[58:61], v[142:145], v[176:179], v[58:61]
	v_mfma_f32_16x16x32_bf16 v[46:49], v[134:137], v[184:187], v[46:49]
	v_mfma_f32_16x16x32_bf16 v[42:45], v[142:145], v[184:187], v[42:45]
	v_mfma_f32_16x16x32_bf16 v[30:33], v[134:137], v[192:195], v[30:33]
	v_mfma_f32_16x16x32_bf16 v[26:29], v[142:145], v[192:195], v[26:29]
	v_mfma_f32_16x16x32_bf16 v[14:17], v[134:137], v[200:203], v[14:17]
	v_mfma_f32_16x16x32_bf16 v[10:13], v[142:145], v[200:203], v[10:13]
	s_setprio 0
	s_setprio 1
	v_mfma_f32_16x16x32_bf16 v[54:57], v[146:149], v[172:175], v[54:57]
	v_mfma_f32_16x16x32_bf16 v[50:53], v[154:157], v[172:175], v[50:53]
	v_mfma_f32_16x16x32_bf16 v[38:41], v[146:149], v[180:183], v[38:41]
	v_mfma_f32_16x16x32_bf16 v[34:37], v[154:157], v[180:183], v[34:37]
	v_mfma_f32_16x16x32_bf16 v[22:25], v[146:149], v[188:191], v[22:25]
	v_mfma_f32_16x16x32_bf16 v[18:21], v[154:157], v[188:191], v[18:21]
	v_mfma_f32_16x16x32_bf16 v[6:9], v[146:149], v[196:199], v[6:9]
	v_mfma_f32_16x16x32_bf16 v[2:5], v[154:157], v[196:199], v[2:5]
	v_mfma_f32_16x16x32_bf16 v[54:57], v[150:153], v[176:179], v[54:57]
	v_mfma_f32_16x16x32_bf16 v[50:53], v[168:171], v[176:179], v[50:53]
	v_mfma_f32_16x16x32_bf16 v[38:41], v[150:153], v[184:187], v[38:41]
	v_mfma_f32_16x16x32_bf16 v[34:37], v[168:171], v[184:187], v[34:37]
	v_mfma_f32_16x16x32_bf16 v[22:25], v[150:153], v[192:195], v[22:25]
	v_mfma_f32_16x16x32_bf16 v[18:21], v[168:171], v[192:195], v[18:21]
	v_mfma_f32_16x16x32_bf16 v[6:9], v[150:153], v[200:203], v[6:9]
	v_mfma_f32_16x16x32_bf16 v[2:5], v[168:171], v[200:203], v[2:5]
	s_barrier
	s_setprio 0
	s_add_i32 s39, s39, 2
	s_add_u32 s46, s46, 0x1000
	s_addc_u32 s47, s47, 0
	s_add_u32 s36, s36, 0x100
	s_addc_u32 s37, s37, 0
	s_cmpk_gt_u32 s39, 0x7d
	s_cbranch_scc0 .LBB0_882
	s_and_b64 vcc, exec, s[8:9]
	s_cbranch_vccz .LBB0_885
	s_barrier

; #define LAS __attribute__((address_space(3)))
; #define ARGS() KArgs* ap = (KArgs*)__builtin_amdgcn_kernarg_segment_ptr(); asm volatile("" : "+s"(ap)); unsigned char* ws = ap->ws; (void)ws
; __global__ void __launch_bounds__(512, 2) fwd_megakernel(Args a_unused) {
;     ...
;         if (l + 1 < DEPTH) {
;             ARGS();
;             pg8::Gemm g{(const bf16_t*)(ws + WS_Z), (const bf16_t*)(ws + WS_W + (size_t)l * LW + OW_2), FF, FF, 0, 0, nullptr, nullptr}; pg8::StaticOrder S; S.init(M, D, G, vcu); S.revr = true;
;             bf16_t* R1 = (bf16_t*)ap->out; bf16_t* R2 = R1 + SEC;
;             EpiResid E{(const void*)R1, (void*)R2, (float*)(ws + WS_SSP) + (size_t)(2 * l + 2) * M * 8, true, false, (LAS float*)(lds + 131072 + 1024)};
;             pg8::gemm_phase<EpiResid>(lds, g, S, E, wave_s);
.LBB0_986:
	s_and_b64 vcc, exec, s[2:3]
	s_cbranch_vccz .LBB0_98
	s_mov_b64 s[100:101], 0x800
	s_mov_b64 s[4:5], s[66:67]
	v_mbcnt_lo_u32_b32 v0, -1, 0
	v_mbcnt_hi_u32_b32 v0, -1, v0
	s_and_b64 vcc, exec, s[22:23]
	v_add_u32_e32 v11, s81, v0
	s_nop 0
	v_readfirstlane_b32 s12, v11
	s_cbranch_vccnz .LBB0_991
	v_readlane_b32 s2, v254, 40
	v_readlane_b32 s3, v254, 41
	s_andn2_b64 vcc, exec, s[2:3]
	v_readlane_b32 s2, v254, 44
	s_cbranch_vccnz .LBB0_990
	v_readlane_b32 s2, v254, 42

; #define PG8_STAGE(bufoff, gbase, voff) do { _Pragma("unroll") for (int _i = 0; _i < 2; ++_i) \
;         __builtin_amdgcn_global_load_lds((const unsigned*)((const char*)(gbase) + (voff)[_i]), (LAS unsigned*)(lds + (bufoff) + ldsw + _i * 8192), 16, 0, 0); } while (0)
; #define PG8_BAR __builtin_amdgcn_s_barrier()
;     ...
;     const int wid = __builtin_amdgcn_readfirstlane(tid >> 6), lane = tid & 63, wr = wid >> 2, wc = wid & 3, fr = lane & 15, fq = lane >> 4;
;     const int K = g.K, nt = K / BK, lda = g.lda;
;     unsigned voffA[2], voffB[2];
; #pragma unroll
;     for (int i = 0; i < 2; ++i) { int R, C; stage_rc(tid * 16 + i * 8192, R, C); const int Rb = Epi::PERM ? ((R & ~31) + perm32(R & 31)) : R;
;         voffA[i] = (unsigned)(R * lda + C) * 2u; voffB[i] = (unsigned)(Rb * K + C) * 2u; }
;     const size_t kstep = (size_t)(BK * 2);
;     const size_t hstepA = (size_t)HALF * lda * 2, hstepB = (size_t)HALF * K * 2;
;     const size_t tstepA = 2 * hstepA, tstepB = 2 * hstepB;
;     const unsigned ldsw = (unsigned)wid * 1024u;
;     const int aoff = lds_byte(wr * 64 + fr, fq * 8), boff = lds_byte(wc * 32 + fr, fq * 8);
;     ...
;     Unit cur, nxt; int ui = 0;
;     if (!S.next(0, cur)) return;
;     f32x4 acc[2][2][4][2];
; #pragma unroll
;     for (int a = 0; a < 2; ++a)
; #pragma unroll
;         for (int b = 0; b < 2; ++b)
; #pragma unroll
;             for (int m = 0; m < 4; ++m)
; #pragma unroll
;                 for (int n = 0; n < 2; ++n) acc[a][b][m][n] = (f32x4){0.f, 0.f, 0.f, 0.f};
;     bf16x8 At[4][2], B0[2][2], B1[2][2];
;     const char* cA = (const char*)g.A + (size_t)cur.pm * tstepA + (size_t)((cur.pn >> g.ash) * g.amul) * 2; const char* cB = (const char*)g.Bt + (size_t)cur.pn * tstepB;
;     PG8_STAGE(PG8_SB(0, 0), cB, voffB); PG8_STAGE(PG8_SB(0, 1), cB + hstepB, voffB); PG8_STAGE(PG8_SA(0, 0), cA, voffA); PG8_STAGE(PG8_SA(0, 1), cA + hstepA, voffA);
;     if (wr == 1) PG8_BAR;
.LBB0_991:
	s_load_dwordx4 s[44:47], s[4:5], 0x98
	s_and_b64 vcc, exec, s[22:23]
	s_cbranch_vccnz .LBB0_1029
	v_ashrrev_i32_e32 v0, 31, v11
	v_lshrrev_b32_e32 v0, 26, v0
	v_add_u32_e32 v0, v11, v0
	v_ashrrev_i32_e32 v10, 6, v0
	v_bfe_i32 v0, v11, 27, 1
	v_lshlrev_b32_e32 v2, 4, v11
	v_lshrrev_b32_e32 v0, 22, v0
	v_add_u32_e32 v0, v2, v0
	v_and_b32_e32 v0, 0xfffffc00, v0
	v_sub_u32_e32 v0, v2, v0
	v_lshrrev_b32_e32 v3, 4, v0
	v_bitop3_b32 v0, v3, v0, 32 bitop3:0x6c
	v_ashrrev_i32_e32 v4, 31, v0
	v_lshrrev_b32_e32 v4, 26, v4
	s_waitcnt lgkmcnt(0)
	s_add_u32 s25, s46, 0x12800000
	v_add_u32_e32 v4, v0, v4
	s_addc_u32 s28, s47, 0
	v_readlane_b32 s3, v254, 55
	v_lshlrev_b32_e32 v3, 3, v10
	v_ashrrev_i32_e32 v12, 6, v4
	v_and_b32_e32 v4, 0xc0, v4
	s_add_u32 s3, s46, s3
	v_and_b32_e32 v3, -16, v3
	v_sub_u32_e32 v0, v0, v4
	s_addc_u32 s4, s47, 0
	v_add_u32_e32 v3, v12, v3
	v_ashrrev_i16_sdwa v0, v227, sext(v0) dst_sel:DWORD dst_unused:UNUSED_PAD src0_sel:DWORD src1_sel:BYTE_0
	s_add_u32 s29, s3, 0x7400000
	v_lshlrev_b32_e32 v5, 5, v10
	v_bfe_i32 v13, v0, 0, 16
	v_lshlrev_b32_e32 v0, 1, v3
	v_lshrrev_b32_e32 v4, 2, v3
	v_and_b32_e32 v6, 3, v12
	s_mov_b32 s3, 0x3ffe0
	v_and_b32_e32 v5, 32, v5
	v_and_b32_e32 v0, 24, v0
	v_and_b32_e32 v4, 4, v4
	v_and_or_b32 v6, v3, s3, v6
	v_or3_b32 v0, v6, v4, v0
	v_add_lshl_u32 v4, v5, v13, 1
	v_add_u32_e32 v2, 0x2000, v2
	v_lshl_add_u32 v154, v3, 14, v4
	v_lshrrev_b32_e32 v255, 14, v154
	v_and_b32_e32 v250, 0x3fff, v154
	v_and_b32_e32 v154, 0xfffffff0, v255
	v_lshlrev_b32_e32 v154, 14, v154
	v_and_b32_e32 v255, 15, v255
	v_lshl_add_u32 v154, v255, 6, v154
	v_and_b32_e32 v255, 64, v250
	v_lshl_add_u32 v154, v255, 4, v154
	v_and_b32_e32 v250, 63, v250
	v_add_u32_e32 v154, v154, v250
	v_ashrrev_i32_e32 v3, 31, v2
	v_lshrrev_b32_e32 v3, 22, v3
	v_add_u32_e32 v3, v2, v3
	v_ashrrev_i32_e32 v14, 10, v3
	v_mul_i32_i24_e32 v3, 0x400, v14
	v_sub_u32_e32 v2, v2, v3
	v_lshrrev_b32_e32 v3, 4, v2
	v_bitop3_b32 v2, v3, v2, 32 bitop3:0x6c
	v_lshl_add_u32 v0, v0, 14, v4
	v_ashrrev_i32_e32 v4, 31, v2
	v_lshrrev_b32_e32 v4, 26, v4
	v_lshlrev_b32_e32 v3, 3, v14
	v_add_u32_e32 v4, v2, v4
	v_and_b32_e32 v3, -16, v3
	v_ashrrev_i32_e32 v15, 6, v4
	v_add_u32_e32 v3, v15, v3
	v_and_b32_e32 v6, 3, v15
	s_addc_u32 s56, s4, 0
	s_ashr_i32 s10, s12, 6
	v_and_b32_e32 v4, 0xc0, v4
	v_and_or_b32 v6, v3, s3, v6
	s_ashr_i32 s21, s20, 31
	s_ashr_i32 s3, s2, 31
	v_sub_u32_e32 v2, v2, v4
	s_ashr_i32 s11, s12, 8
	s_lshl_b32 s57, s10, 10
	s_lshl_b64 s[4:5], s[20:21], 22
	s_lshl_b64 s[6:7], s[2:3], 22
	v_ashrrev_i16_sdwa v2, v227, sext(v2) dst_sel:DWORD dst_unused:UNUSED_PAD src0_sel:DWORD src1_sel:BYTE_0
	s_add_u32 s48, s29, s6
	v_lshlrev_b32_e32 v5, 5, v14
	v_bfe_i32 v16, v2, 0, 16
	v_lshlrev_b32_e32 v2, 1, v3
	v_lshrrev_b32_e32 v4, 2, v3
	s_addc_u32 s49, s56, s7
	s_add_i32 s60, s57, 0
	v_and_b32_e32 v5, 32, v5
	v_and_b32_e32 v2, 24, v2
	v_and_b32_e32 v4, 4, v4
	s_add_i32 m0, s60, 0x10000
	v_or3_b32 v2, v6, v4, v2
	v_add_lshl_u32 v4, v5, v16, 1
	global_load_lds_dwordx4 v0, s[48:49]
	s_add_i32 m0, s60, 0x12000
	v_lshl_add_u32 v158, v2, 14, v4
	s_add_u32 s6, s48, 0x200000
	global_load_lds_dwordx4 v158, s[48:49]
	s_addc_u32 s7, s49, 0
	s_add_i32 m0, s60, 0x14000
	v_lshl_add_u32 v156, v3, 14, v4
	v_lshrrev_b32_e32 v255, 14, v156
	v_and_b32_e32 v250, 0x3fff, v156
	v_and_b32_e32 v156, 0xfffffff0, v255
	v_lshlrev_b32_e32 v156, 14, v156
	v_and_b32_e32 v255, 15, v255
	v_lshl_add_u32 v156, v255, 6, v156
	v_and_b32_e32 v255, 64, v250
	v_lshl_add_u32 v156, v255, 4, v156
	v_and_b32_e32 v250, 63, v250
	v_add_u32_e32 v156, v156, v250
	global_load_lds_dwordx4 v0, s[6:7]
	s_add_i32 m0, s60, 0x16000
	s_add_u32 s50, s25, s4
	s_addc_u32 s51, s28, s5
	s_add_i32 s61, s60, 0x2000
	global_load_lds_dwordx4 v158, s[6:7]
	s_mov_b32 m0, s60
	s_add_u32 s4, s50, 0x200000
	global_load_lds_dwordx4 v154, s[50:51]
	s_mov_b32 m0, s61
	s_addc_u32 s5, s51, 0
	s_add_i32 s62, s60, 0x4000
	global_load_lds_dwordx4 v156, s[50:51]
	s_mov_b32 m0, s62
	s_add_i32 s63, s60, 0x6000
	global_load_lds_dwordx4 v154, s[4:5]
	s_mov_b32 m0, s63
	v_mov_b32_e32 v159, v1
	global_load_lds_dwordx4 v156, s[4:5]
	v_mov_b32_e32 v155, v1
	v_mov_b32_e32 v157, v1
	s_cmp_eq_u32 s11, 1
	v_lshl_add_u64 v[8:9], s[48:49], 0, v[0:1]
	v_lshl_add_u64 v[6:7], s[48:49], 0, v[158:159]
	v_lshl_add_u64 v[2:3], s[50:51], 0, v[154:155]
	s_cselect_b64 s[4:5], -1, 0
	s_cmp_lg_u32 s11, 1
	v_lshl_add_u64 v[4:5], s[50:51], 0, v[156:157]
	s_cbranch_scc1 .LBB0_994
	s_barrier
; #define PG8_STAGE(bufoff, gbase, voff) do { _Pragma("unroll") for (int _i = 0; _i < 2; ++_i) \
;         __builtin_amdgcn_global_load_lds((const unsigned*)((const char*)(gbase) + (voff)[_i]), (LAS unsigned*)(lds + (bufoff) + ldsw + _i * 8192), 16, 0, 0); } while (0)
; #define PG8_WAIT_V(n) asm volatile("s_waitcnt vmcnt(" #n ")" ::: "memory")
; #define PG8_BAR __builtin_amdgcn_s_barrier()
;     ...
;     if (wr == 1) PG8_BAR;
;     PG8_WAIT_V(2); PG8_BAR;
;     PG8_STAGE(PG8_SB(1, 0), cB + kstep, voffB); PG8_STAGE(PG8_SA(1, 0), cA + kstep, voffA); PG8_STAGE(PG8_SB(1, 1), cB + hstepB + kstep, voffB);
;     PG8_WAIT_V(6); PG8_BAR;
.LBB0_994:
	s_add_u32 s6, s44, 0x4000000
	s_addc_u32 s7, s45, 0
	v_bfe_u32 v17, v11, 4, 2
	s_add_u32 s8, s46, 0x36d00000
	v_and_b32_e32 v18, 15, v11
	v_lshlrev_b32_e32 v20, 4, v17
	v_lshlrev_b32_e32 v11, 2, v11
	s_addc_u32 s9, s47, 0
	s_and_b32 s13, s10, 3
	v_lshl_or_b32 v21, v18, 6, v20
	s_lshl_b32 s3, s11, 13
	v_and_b32_e32 v11, 32, v11
	s_add_i32 m0, s60, 0x18000
	v_lshl_add_u64 v[8:9], v[8:9], 0, s[34:35]
	v_bitop3_b32 v22, v21, s3, v11 bitop3:0xde
	s_lshl_b32 s3, s13, 12
	s_waitcnt vmcnt(2)
	s_barrier
	global_load_lds_dwordx4 v[8:9], off
	v_lshl_add_u64 v[6:7], v[6:7], 0, s[34:35]
	s_add_i32 m0, s60, 0x1a000
	s_add_i32 s74, s60, 0x8000
	s_add_i32 s75, s60, 0xa000
	global_load_lds_dwordx4 v[6:7], off
	v_lshl_add_u64 v[2:3], v[2:3], 0, s[100:101]
	s_mov_b32 m0, s74
	s_add_u32 s10, s48, 0x200080
	v_lshl_or_b32 v176, s11, 6, v18
	global_load_lds_dwordx4 v[2:3], off
	v_lshl_add_u64 v[2:3], v[4:5], 0, s[100:101]
	s_mov_b32 m0, s75
	s_addc_u32 s11, s49, 0
	global_load_lds_dwordx4 v[2:3], off
	s_add_i32 m0, s60, 0x1c000
	v_lshl_add_u64 v[2:3], s[10:11], 0, v[0:1]
	global_load_lds_dwordx4 v[2:3], off
	v_lshl_add_u64 v[2:3], s[10:11], 0, v[158:159]
	s_add_i32 m0, s60, 0x1e000
	s_cmpk_lt_u32 s12, 0x100
	global_load_lds_dwordx4 v[2:3], off
	v_lshlrev_b32_e32 v3, 17, v10
	v_and_b32_e32 v3, 0xfffc0000, v3
	s_cselect_b64 s[10:11], -1, 0
	s_and_b32 s12, s12, 0xffffff00
	s_lshl_b32 s14, s13, 6
	v_lshl_add_u32 v3, v12, 14, v3
	v_and_b32_e32 v4, 1, v10
	s_or_b32 s12, s14, s12
	v_lshl_or_b32 v3, v4, 6, v3
	v_or3_b32 v179, s12, v20, v18
	s_movk_i32 s12, 0x100
	v_lshl_add_u32 v160, v13, 1, v3
	v_lshrrev_b32_e32 v255, 14, v160
	v_and_b32_e32 v250, 0x3fff, v160
	v_and_b32_e32 v160, 0xfffffff0, v255
	v_lshlrev_b32_e32 v160, 14, v160
	v_and_b32_e32 v255, 15, v255
	v_lshl_add_u32 v160, v255, 6, v160
	v_and_b32_e32 v255, 64, v250
	v_lshl_add_u32 v160, v255, 4, v160
	v_and_b32_e32 v250, 63, v250
	v_add_u32_e32 v160, v160, v250
	v_lshlrev_b32_e32 v3, 17, v14
	v_cmp_gt_i32_e64 s[40:41], s12, v179
	s_lshl_b32 s12, s13, 2
	v_and_b32_e32 v3, 0xfffc0000, v3
	s_waitcnt vmcnt(6)
	v_lshlrev_b32_e32 v2, 4, v179
	s_add_i32 s12, s12, 0
	v_lshl_add_u32 v3, v15, 14, v3
	v_and_b32_e32 v4, 1, v14
	v_lshlrev_b32_e32 v19, 3, v17
	s_add_i32 s12, s12, 0x20400
	v_lshl_or_b32 v3, v4, 6, v3
	v_add_u32_e32 v2, 0, v2
	v_readlane_b32 s64, v254, 37
	v_bitop3_b32 v177, v21, s3, v11 bitop3:0xde
	v_lshl_or_b32 v178, s13, 5, v19
	s_mov_b32 s3, 0
	v_cmp_eq_u32_e64 s[38:39], 0, v17
	v_lshl_add_u32 v180, v176, 4, s12
	v_mov_b32_e32 v161, v1
	v_lshl_add_u32 v162, v16, 1, v3
	v_lshrrev_b32_e32 v255, 14, v162
	v_and_b32_e32 v250, 0x3fff, v162
	v_and_b32_e32 v162, 0xfffffff0, v255
	v_lshlrev_b32_e32 v162, 14, v162
	v_and_b32_e32 v255, 15, v255
	v_lshl_add_u32 v162, v255, 6, v162
	v_and_b32_e32 v255, 64, v250
	v_lshl_add_u32 v162, v255, 4, v162
	v_and_b32_e32 v250, 63, v250
	v_add_u32_e32 v162, v162, v250
	v_mov_b32_e32 v163, v1
	v_add_u32_e32 v181, 0, v22
	v_add_u32_e32 v182, 0x20400, v2
	v_readlane_b32 s65, v254, 38
	s_barrier
	s_branch .LBB0_997

; #define PG8_BAR __builtin_amdgcn_s_barrier()
;     ...
;         const bool has_next = S.next(ui + 1, nxt);
;         const char* nA = has_next ? (const char*)g.A + (size_t)nxt.pm * tstepA + (size_t)((nxt.pn >> g.ash) * g.amul) * 2 : cA; const char* nB = has_next ? (const char*)g.Bt + (size_t)nxt.pn * tstepB : cB;
;         PG8_KLOOP();
;         if (wr == 0) PG8_BAR;
;         E(acc, cur, wr, wc, fr, fq);
;         if (!has_next) break;
; #pragma unroll
;         for (int a = 0; a < 2; ++a)
; #pragma unroll
;             for (int b = 0; b < 2; ++b)
; #pragma unroll
;                 for (int m = 0; m < 4; ++m)
; #pragma unroll
;                     for (int n = 0; n < 2; ++n) acc[a][b][m][n] = (f32x4){0.f, 0.f, 0.f, 0.f};
;         cur = nxt; cA = nA; cB = nB; ++ui;
.LBB0_1003:
	s_ashr_i32 s15, s14, 31
	s_lshl_b64 s[16:17], s[14:15], 22
	s_add_u32 s16, s25, s16
	s_addc_u32 s17, s28, s17
	s_and_b64 s[18:19], s[42:43], exec
	s_cselect_b32 s3, s17, s51
	s_cselect_b32 s15, s16, s50
	s_ashr_i32 s13, s12, 31
	s_lshl_b64 s[18:19], s[12:13], 22
	s_add_u32 s18, s29, s18
	s_addc_u32 s19, s56, s19
	s_and_b64 s[22:23], s[42:43], exec
	s_cselect_b32 s13, s19, s49
	s_cselect_b32 s21, s18, s48
	s_add_u32 s46, s50, 0x200800
	s_addc_u32 s47, s51, 0
	s_add_u32 s36, s48, 0x100
	v_mov_b32_e32 v2, 0
	s_addc_u32 s37, s49, 0
	s_mov_b32 s48, -2
	v_mov_b32_e32 v3, v2
	v_mov_b32_e32 v4, v2
	v_mov_b32_e32 v5, v2
	v_mov_b32_e32 v6, v2
	v_mov_b32_e32 v7, v2
	v_mov_b32_e32 v8, v2
	v_mov_b32_e32 v9, v2
	v_mov_b32_e32 v18, v2
	v_mov_b32_e32 v19, v2
	v_mov_b32_e32 v20, v2
	v_mov_b32_e32 v21, v2
	v_mov_b32_e32 v22, v2
	v_mov_b32_e32 v23, v2
	v_mov_b32_e32 v24, v2
	v_mov_b32_e32 v25, v2
	v_mov_b32_e32 v34, v2
	v_mov_b32_e32 v35, v2
	v_mov_b32_e32 v36, v2
	v_mov_b32_e32 v37, v2
	v_mov_b32_e32 v38, v2
	v_mov_b32_e32 v39, v2
	v_mov_b32_e32 v40, v2
	v_mov_b32_e32 v41, v2
	v_mov_b32_e32 v50, v2
	v_mov_b32_e32 v51, v2
	v_mov_b32_e32 v52, v2
	v_mov_b32_e32 v53, v2
	v_mov_b32_e32 v54, v2
	v_mov_b32_e32 v55, v2
	v_mov_b32_e32 v56, v2
	v_mov_b32_e32 v57, v2
	v_mov_b32_e32 v10, v2
	v_mov_b32_e32 v11, v2
	v_mov_b32_e32 v12, v2
	v_mov_b32_e32 v13, v2
	v_mov_b32_e32 v14, v2
	v_mov_b32_e32 v15, v2
	v_mov_b32_e32 v16, v2
	v_mov_b32_e32 v17, v2
	v_mov_b32_e32 v26, v2
	v_mov_b32_e32 v27, v2
	v_mov_b32_e32 v28, v2
	v_mov_b32_e32 v29, v2
	v_mov_b32_e32 v30, v2
	v_mov_b32_e32 v31, v2
	v_mov_b32_e32 v32, v2
	v_mov_b32_e32 v33, v2
	v_mov_b32_e32 v42, v2
	v_mov_b32_e32 v43, v2
	v_mov_b32_e32 v44, v2
	v_mov_b32_e32 v45, v2
	v_mov_b32_e32 v46, v2
	v_mov_b32_e32 v47, v2
	v_mov_b32_e32 v48, v2
	v_mov_b32_e32 v49, v2
	v_mov_b32_e32 v58, v2
	v_mov_b32_e32 v59, v2
	v_mov_b32_e32 v60, v2
	v_mov_b32_e32 v61, v2
	v_mov_b32_e32 v62, v2
	v_mov_b32_e32 v63, v2
	v_mov_b32_e32 v64, v2
	v_mov_b32_e32 v65, v2
	v_mov_b32_e32 v66, v2
	v_mov_b32_e32 v67, v2
	v_mov_b32_e32 v68, v2
	v_mov_b32_e32 v69, v2
	v_mov_b32_e32 v70, v2
	v_mov_b32_e32 v71, v2
	v_mov_b32_e32 v72, v2
	v_mov_b32_e32 v73, v2
	v_mov_b32_e32 v82, v2
	v_mov_b32_e32 v83, v2
	v_mov_b32_e32 v84, v2
	v_mov_b32_e32 v85, v2
	v_mov_b32_e32 v86, v2
	v_mov_b32_e32 v87, v2
	v_mov_b32_e32 v88, v2
	v_mov_b32_e32 v89, v2
	v_mov_b32_e32 v98, v2
	v_mov_b32_e32 v99, v2
	v_mov_b32_e32 v100, v2
	v_mov_b32_e32 v101, v2
	v_mov_b32_e32 v102, v2
	v_mov_b32_e32 v103, v2
	v_mov_b32_e32 v104, v2
	v_mov_b32_e32 v105, v2
	v_mov_b32_e32 v114, v2
	v_mov_b32_e32 v115, v2
	v_mov_b32_e32 v116, v2
	v_mov_b32_e32 v117, v2
	v_mov_b32_e32 v118, v2
	v_mov_b32_e32 v119, v2
	v_mov_b32_e32 v120, v2
	v_mov_b32_e32 v121, v2
	v_mov_b32_e32 v74, v2
	v_mov_b32_e32 v75, v2
	v_mov_b32_e32 v76, v2
	v_mov_b32_e32 v77, v2
	v_mov_b32_e32 v78, v2
	v_mov_b32_e32 v79, v2
	v_mov_b32_e32 v80, v2
	v_mov_b32_e32 v81, v2
	v_mov_b32_e32 v90, v2
	v_mov_b32_e32 v91, v2
	v_mov_b32_e32 v92, v2
	v_mov_b32_e32 v93, v2
	v_mov_b32_e32 v94, v2
	v_mov_b32_e32 v95, v2
	v_mov_b32_e32 v96, v2
	v_mov_b32_e32 v97, v2
	v_mov_b32_e32 v106, v2
	v_mov_b32_e32 v107, v2
	v_mov_b32_e32 v108, v2
	v_mov_b32_e32 v109, v2
	v_mov_b32_e32 v110, v2
	v_mov_b32_e32 v111, v2
	v_mov_b32_e32 v112, v2
	v_mov_b32_e32 v113, v2
	v_mov_b32_e32 v122, v2
	v_mov_b32_e32 v123, v2
	v_mov_b32_e32 v124, v2
	v_mov_b32_e32 v125, v2
	v_mov_b32_e32 v126, v2
	v_mov_b32_e32 v127, v2
	v_mov_b32_e32 v128, v2
	v_mov_b32_e32 v129, v2
.LBB0_1004:
	s_add_u32 s22, s46, 0xffe00800
	s_addc_u32 s23, s47, -1
	s_add_i32 s24, 0, 0x10000
	s_cmpk_eq_i32 s48, 0x7c
	s_cselect_b32 s23, s3, s23
	s_cselect_b32 s22, s15, s22
	s_cselect_b32 s27, s13, s37
	s_cselect_b32 s26, s21, s36
	s_add_i32 s49, 0, 0x14000
	v_add_u32_e32 v142, s24, v177
	v_add_u32_e32 v168, s49, v177
	ds_read_b128 v[130:133], v142
	ds_read_b128 v[134:137], v142 offset:1024
	ds_read_b128 v[138:141], v142 offset:2048
	ds_read_b128 v[142:145], v142 offset:3072
	ds_read_b128 v[146:149], v168
	ds_read_b128 v[150:153], v168 offset:1024
	ds_read_b128 v[164:167], v168 offset:2048
	ds_read_b128 v[168:171], v168 offset:3072
	v_lshl_add_u64 v[212:213], s[46:47], 0, v[160:161]
	s_add_i32 m0, s60, 0xc000
	ds_read_b128 v[172:175], v181
	ds_read_b128 v[184:187], v181 offset:1024
	ds_read_b128 v[188:191], v181 offset:2048
	ds_read_b128 v[192:195], v181 offset:3072
	ds_read_b128 v[196:199], v181 offset:4096
	ds_read_b128 v[200:203], v181 offset:5120
	ds_read_b128 v[204:207], v181 offset:6144
	ds_read_b128 v[208:211], v181 offset:7168
	global_load_lds_dwordx4 v[212:213], off
	v_lshl_add_u64 v[212:213], s[46:47], 0, v[162:163]
	s_add_i32 m0, s60, 0xe000
	s_nop 0
	global_load_lds_dwordx4 v[212:213], off
	s_waitcnt vmcnt(8)
	s_waitcnt lgkmcnt(0)
	s_setprio 1
	s_barrier
	v_mfma_f32_16x16x32_bf16 v[126:129], v[130:133], v[172:175], v[126:129]
	v_mfma_f32_16x16x32_bf16 v[122:125], v[138:141], v[172:175], v[122:125]
	v_mfma_f32_16x16x32_bf16 v[110:113], v[130:133], v[188:191], v[110:113]
	v_mfma_f32_16x16x32_bf16 v[106:109], v[138:141], v[188:191], v[106:109]
	v_mfma_f32_16x16x32_bf16 v[94:97], v[130:133], v[196:199], v[94:97]
	v_mfma_f32_16x16x32_bf16 v[90:93], v[138:141], v[196:199], v[90:93]
	v_mfma_f32_16x16x32_bf16 v[78:81], v[130:133], v[204:207], v[78:81]
	v_mfma_f32_16x16x32_bf16 v[74:77], v[138:141], v[204:207], v[74:77]
	v_mfma_f32_16x16x32_bf16 v[126:129], v[134:137], v[184:187], v[126:129]
	v_mfma_f32_16x16x32_bf16 v[122:125], v[142:145], v[184:187], v[122:125]
	v_mfma_f32_16x16x32_bf16 v[110:113], v[134:137], v[192:195], v[110:113]
	v_mfma_f32_16x16x32_bf16 v[106:109], v[142:145], v[192:195], v[106:109]
	v_mfma_f32_16x16x32_bf16 v[94:97], v[134:137], v[200:203], v[94:97]
	v_mfma_f32_16x16x32_bf16 v[90:93], v[142:145], v[200:203], v[90:93]
	v_mfma_f32_16x16x32_bf16 v[78:81], v[134:137], v[208:211], v[78:81]
	v_mfma_f32_16x16x32_bf16 v[74:77], v[142:145], v[208:211], v[74:77]
	s_setprio 0
	s_setprio 1
	v_mfma_f32_16x16x32_bf16 v[118:121], v[146:149], v[172:175], v[118:121]
	v_mfma_f32_16x16x32_bf16 v[114:117], v[164:167], v[172:175], v[114:117]
	v_mfma_f32_16x16x32_bf16 v[102:105], v[146:149], v[188:191], v[102:105]
	v_mfma_f32_16x16x32_bf16 v[98:101], v[164:167], v[188:191], v[98:101]
	v_mfma_f32_16x16x32_bf16 v[86:89], v[146:149], v[196:199], v[86:89]
	v_mfma_f32_16x16x32_bf16 v[82:85], v[164:167], v[196:199], v[82:85]
	v_mfma_f32_16x16x32_bf16 v[70:73], v[146:149], v[204:207], v[70:73]
	v_mfma_f32_16x16x32_bf16 v[66:69], v[164:167], v[204:207], v[66:69]
	v_mfma_f32_16x16x32_bf16 v[118:121], v[150:153], v[184:187], v[118:121]
	v_mfma_f32_16x16x32_bf16 v[114:117], v[168:171], v[184:187], v[114:117]
	v_mfma_f32_16x16x32_bf16 v[102:105], v[150:153], v[192:195], v[102:105]
	v_mfma_f32_16x16x32_bf16 v[98:101], v[168:171], v[192:195], v[98:101]
	v_mfma_f32_16x16x32_bf16 v[86:89], v[150:153], v[200:203], v[86:89]
	v_mfma_f32_16x16x32_bf16 v[82:85], v[168:171], v[200:203], v[82:85]
	v_mfma_f32_16x16x32_bf16 v[70:73], v[150:153], v[208:211], v[70:73]
	v_mfma_f32_16x16x32_bf16 v[66:69], v[168:171], v[208:211], v[66:69]
	s_barrier
	s_setprio 0
	s_add_i32 s24, s24, s57
	v_lshl_add_u64 v[212:213], s[26:27], 0, v[0:1]
	s_mov_b32 m0, s24
	ds_read_b128 v[172:175], v181 offset:16384
	ds_read_b128 v[184:187], v181 offset:17408
	ds_read_b128 v[188:191], v181 offset:18432
	ds_read_b128 v[192:195], v181 offset:19456
	ds_read_b128 v[196:199], v181 offset:20480
	ds_read_b128 v[200:203], v181 offset:21504
	ds_read_b128 v[204:207], v181 offset:22528
	ds_read_b128 v[208:211], v181 offset:23552
	global_load_lds_dwordx4 v[212:213], off
	s_add_i32 m0, s24, 0x2000
	s_add_u32 s50, s26, 0x200000
	v_lshl_add_u64 v[214:215], s[26:27], 0, v[158:159]
	s_addc_u32 s51, s27, 0
	s_add_i32 s24, s49, s57
	global_load_lds_dwordx4 v[214:215], off
	v_lshl_add_u64 v[216:217], s[50:51], 0, v[0:1]
	s_mov_b32 m0, s24
	v_lshl_add_u64 v[218:219], s[22:23], 0, v[156:157]
	global_load_lds_dwordx4 v[216:217], off
	v_lshl_add_u64 v[216:217], s[50:51], 0, v[158:159]
	s_add_i32 m0, s24, 0x2000
	s_nop 0
	global_load_lds_dwordx4 v[216:217], off
	v_lshl_add_u64 v[216:217], s[22:23], 0, v[154:155]
	s_mov_b32 m0, s60
	s_nop 0
	global_load_lds_dwordx4 v[216:217], off
	s_mov_b32 m0, s61
	s_nop 0
	global_load_lds_dwordx4 v[218:219], off
	s_waitcnt vmcnt(8)
	s_waitcnt lgkmcnt(0)
	s_setprio 1
	s_barrier
	v_mfma_f32_16x16x32_bf16 v[62:65], v[130:133], v[172:175], v[62:65]
	v_mfma_f32_16x16x32_bf16 v[58:61], v[138:141], v[172:175], v[58:61]
	v_mfma_f32_16x16x32_bf16 v[46:49], v[130:133], v[188:191], v[46:49]
	v_mfma_f32_16x16x32_bf16 v[42:45], v[138:141], v[188:191], v[42:45]
	v_mfma_f32_16x16x32_bf16 v[30:33], v[130:133], v[196:199], v[30:33]
	v_mfma_f32_16x16x32_bf16 v[26:29], v[138:141], v[196:199], v[26:29]
	v_mfma_f32_16x16x32_bf16 v[14:17], v[130:133], v[204:207], v[14:17]
	v_mfma_f32_16x16x32_bf16 v[10:13], v[138:141], v[204:207], v[10:13]
	v_mfma_f32_16x16x32_bf16 v[62:65], v[134:137], v[184:187], v[62:65]
	v_mfma_f32_16x16x32_bf16 v[58:61], v[142:145], v[184:187], v[58:61]
	v_mfma_f32_16x16x32_bf16 v[46:49], v[134:137], v[192:195], v[46:49]
	v_mfma_f32_16x16x32_bf16 v[42:45], v[142:145], v[192:195], v[42:45]
	v_mfma_f32_16x16x32_bf16 v[30:33], v[134:137], v[200:203], v[30:33]
	v_mfma_f32_16x16x32_bf16 v[26:29], v[142:145], v[200:203], v[26:29]
	v_mfma_f32_16x16x32_bf16 v[14:17], v[134:137], v[208:211], v[14:17]
	v_mfma_f32_16x16x32_bf16 v[10:13], v[142:145], v[208:211], v[10:13]
	s_setprio 0
	s_setprio 1
	v_mfma_f32_16x16x32_bf16 v[54:57], v[146:149], v[172:175], v[54:57]
	v_mfma_f32_16x16x32_bf16 v[50:53], v[164:167], v[172:175], v[50:53]
	v_mfma_f32_16x16x32_bf16 v[38:41], v[146:149], v[188:191], v[38:41]
	v_mfma_f32_16x16x32_bf16 v[34:37], v[164:167], v[188:191], v[34:37]
	v_mfma_f32_16x16x32_bf16 v[22:25], v[146:149], v[196:199], v[22:25]
	v_mfma_f32_16x16x32_bf16 v[18:21], v[164:167], v[196:199], v[18:21]
	v_mfma_f32_16x16x32_bf16 v[6:9], v[146:149], v[204:207], v[6:9]
	v_mfma_f32_16x16x32_bf16 v[2:5], v[164:167], v[204:207], v[2:5]
	v_mfma_f32_16x16x32_bf16 v[54:57], v[150:153], v[184:187], v[54:57]
	v_mfma_f32_16x16x32_bf16 v[50:53], v[168:171], v[184:187], v[50:53]
	v_mfma_f32_16x16x32_bf16 v[38:41], v[150:153], v[192:195], v[38:41]
	v_mfma_f32_16x16x32_bf16 v[34:37], v[168:171], v[192:195], v[34:37]
	v_mfma_f32_16x16x32_bf16 v[22:25], v[150:153], v[200:203], v[22:25]
	v_mfma_f32_16x16x32_bf16 v[18:21], v[168:171], v[200:203], v[18:21]
	v_mfma_f32_16x16x32_bf16 v[6:9], v[150:153], v[208:211], v[6:9]
	v_mfma_f32_16x16x32_bf16 v[2:5], v[168:171], v[208:211], v[2:5]
	s_barrier
	s_setprio 0
	s_add_i32 s24, 0, 0x18000
	s_add_i32 s49, 0, 0x1c000
	v_add_u32_e32 v142, s24, v177
	v_add_u32_e32 v168, s49, v177
	ds_read_b128 v[130:133], v142
	ds_read_b128 v[134:137], v142 offset:1024
	ds_read_b128 v[138:141], v142 offset:2048
	ds_read_b128 v[142:145], v142 offset:3072
	ds_read_b128 v[146:149], v168
	ds_read_b128 v[150:153], v168 offset:1024
	ds_read_b128 v[164:167], v168 offset:2048
	ds_read_b128 v[168:171], v168 offset:3072
	s_add_u32 s22, s22, 0x200000
	s_addc_u32 s23, s23, 0
	s_mov_b32 m0, s62
	v_lshl_add_u64 v[220:221], s[22:23], 0, v[154:155]
	ds_read_b128 v[172:175], v181 offset:32768
	ds_read_b128 v[184:187], v181 offset:33792
	ds_read_b128 v[188:191], v181 offset:34816
	ds_read_b128 v[192:195], v181 offset:35840
	ds_read_b128 v[196:199], v181 offset:36864
	ds_read_b128 v[200:203], v181 offset:37888
	ds_read_b128 v[204:207], v181 offset:38912
	ds_read_b128 v[208:211], v181 offset:39936
	global_load_lds_dwordx4 v[220:221], off
	v_lshl_add_u64 v[220:221], s[22:23], 0, v[156:157]
	s_mov_b32 m0, s63
	s_nop 0
	global_load_lds_dwordx4 v[220:221], off
	s_waitcnt vmcnt(8)
	s_waitcnt lgkmcnt(0)
	s_setprio 1
	s_barrier
	v_mfma_f32_16x16x32_bf16 v[126:129], v[130:133], v[172:175], v[126:129]
	v_mfma_f32_16x16x32_bf16 v[122:125], v[138:141], v[172:175], v[122:125]
	v_mfma_f32_16x16x32_bf16 v[110:113], v[130:133], v[188:191], v[110:113]
	v_mfma_f32_16x16x32_bf16 v[106:109], v[138:141], v[188:191], v[106:109]
	v_mfma_f32_16x16x32_bf16 v[94:97], v[130:133], v[196:199], v[94:97]
	v_mfma_f32_16x16x32_bf16 v[90:93], v[138:141], v[196:199], v[90:93]
	v_mfma_f32_16x16x32_bf16 v[78:81], v[130:133], v[204:207], v[78:81]
	v_mfma_f32_16x16x32_bf16 v[74:77], v[138:141], v[204:207], v[74:77]
	v_mfma_f32_16x16x32_bf16 v[126:129], v[134:137], v[184:187], v[126:129]
	v_mfma_f32_16x16x32_bf16 v[122:125], v[142:145], v[184:187], v[122:125]
	v_mfma_f32_16x16x32_bf16 v[110:113], v[134:137], v[192:195], v[110:113]
	v_mfma_f32_16x16x32_bf16 v[106:109], v[142:145], v[192:195], v[106:109]
	v_mfma_f32_16x16x32_bf16 v[94:97], v[134:137], v[200:203], v[94:97]
	v_mfma_f32_16x16x32_bf16 v[90:93], v[142:145], v[200:203], v[90:93]
	v_mfma_f32_16x16x32_bf16 v[78:81], v[134:137], v[208:211], v[78:81]
	v_mfma_f32_16x16x32_bf16 v[74:77], v[142:145], v[208:211], v[74:77]
	s_setprio 0
	s_setprio 1
	v_mfma_f32_16x16x32_bf16 v[118:121], v[146:149], v[172:175], v[118:121]
	v_mfma_f32_16x16x32_bf16 v[114:117], v[164:167], v[172:175], v[114:117]
	v_mfma_f32_16x16x32_bf16 v[102:105], v[146:149], v[188:191], v[102:105]
	v_mfma_f32_16x16x32_bf16 v[98:101], v[164:167], v[188:191], v[98:101]
	v_mfma_f32_16x16x32_bf16 v[86:89], v[146:149], v[196:199], v[86:89]
	v_mfma_f32_16x16x32_bf16 v[82:85], v[164:167], v[196:199], v[82:85]
	v_mfma_f32_16x16x32_bf16 v[70:73], v[146:149], v[204:207], v[70:73]
	v_mfma_f32_16x16x32_bf16 v[66:69], v[164:167], v[204:207], v[66:69]
	v_mfma_f32_16x16x32_bf16 v[118:121], v[150:153], v[184:187], v[118:121]
	v_mfma_f32_16x16x32_bf16 v[114:117], v[168:171], v[184:187], v[114:117]
	v_mfma_f32_16x16x32_bf16 v[102:105], v[150:153], v[192:195], v[102:105]
	v_mfma_f32_16x16x32_bf16 v[98:101], v[168:171], v[192:195], v[98:101]
	v_mfma_f32_16x16x32_bf16 v[86:89], v[150:153], v[200:203], v[86:89]
	v_mfma_f32_16x16x32_bf16 v[82:85], v[168:171], v[200:203], v[82:85]
	v_mfma_f32_16x16x32_bf16 v[70:73], v[150:153], v[208:211], v[70:73]
	v_mfma_f32_16x16x32_bf16 v[66:69], v[168:171], v[208:211], v[66:69]
	s_barrier
	s_setprio 0
	s_add_i32 s22, s24, s57
	v_lshl_add_u64 v[212:213], v[212:213], 0, s[34:35]
	s_mov_b32 m0, s22
	ds_read_b128 v[172:175], v181 offset:49152
	ds_read_b128 v[184:187], v181 offset:50176
	ds_read_b128 v[188:191], v181 offset:51200
	ds_read_b128 v[192:195], v181 offset:52224
	ds_read_b128 v[196:199], v181 offset:53248
	ds_read_b128 v[200:203], v181 offset:54272
	ds_read_b128 v[204:207], v181 offset:55296
	ds_read_b128 v[208:211], v181 offset:56320
	global_load_lds_dwordx4 v[212:213], off
	s_add_i32 m0, s22, 0x2000
	s_add_u32 s22, s26, 0x200080
	v_lshl_add_u64 v[212:213], v[214:215], 0, s[34:35]
	s_addc_u32 s23, s27, 0
	s_add_i32 s24, s49, s57
	global_load_lds_dwordx4 v[212:213], off
	v_lshl_add_u64 v[212:213], s[22:23], 0, v[0:1]
	s_mov_b32 m0, s24
	s_nop 0
	global_load_lds_dwordx4 v[212:213], off
	v_lshl_add_u64 v[212:213], s[22:23], 0, v[158:159]
	s_add_i32 m0, s24, 0x2000
	s_nop 0
	global_load_lds_dwordx4 v[212:213], off
	v_lshl_add_u64 v[212:213], v[216:217], 0, s[100:101]
	s_mov_b32 m0, s74
	s_nop 0
	global_load_lds_dwordx4 v[212:213], off
	v_lshl_add_u64 v[212:213], v[218:219], 0, s[100:101]
	s_mov_b32 m0, s75
	s_nop 0
	global_load_lds_dwordx4 v[212:213], off
	s_waitcnt vmcnt(8)
	s_waitcnt lgkmcnt(0)
	s_setprio 1
	s_barrier
	v_mfma_f32_16x16x32_bf16 v[62:65], v[130:133], v[172:175], v[62:65]
	v_mfma_f32_16x16x32_bf16 v[58:61], v[138:141], v[172:175], v[58:61]
	v_mfma_f32_16x16x32_bf16 v[46:49], v[130:133], v[188:191], v[46:49]
	v_mfma_f32_16x16x32_bf16 v[42:45], v[138:141], v[188:191], v[42:45]
	v_mfma_f32_16x16x32_bf16 v[30:33], v[130:133], v[196:199], v[30:33]
	v_mfma_f32_16x16x32_bf16 v[26:29], v[138:141], v[196:199], v[26:29]
	v_mfma_f32_16x16x32_bf16 v[14:17], v[130:133], v[204:207], v[14:17]
	v_mfma_f32_16x16x32_bf16 v[10:13], v[138:141], v[204:207], v[10:13]
	v_mfma_f32_16x16x32_bf16 v[62:65], v[134:137], v[184:187], v[62:65]
	v_mfma_f32_16x16x32_bf16 v[58:61], v[142:145], v[184:187], v[58:61]
	v_mfma_f32_16x16x32_bf16 v[46:49], v[134:137], v[192:195], v[46:49]
	v_mfma_f32_16x16x32_bf16 v[42:45], v[142:145], v[192:195], v[42:45]
	v_mfma_f32_16x16x32_bf16 v[30:33], v[134:137], v[200:203], v[30:33]
	v_mfma_f32_16x16x32_bf16 v[26:29], v[142:145], v[200:203], v[26:29]
	v_mfma_f32_16x16x32_bf16 v[14:17], v[134:137], v[208:211], v[14:17]
	v_mfma_f32_16x16x32_bf16 v[10:13], v[142:145], v[208:211], v[10:13]
	s_setprio 0
	s_setprio 1
	v_mfma_f32_16x16x32_bf16 v[54:57], v[146:149], v[172:175], v[54:57]
	v_mfma_f32_16x16x32_bf16 v[50:53], v[164:167], v[172:175], v[50:53]
	v_mfma_f32_16x16x32_bf16 v[38:41], v[146:149], v[188:191], v[38:41]
	v_mfma_f32_16x16x32_bf16 v[34:37], v[164:167], v[188:191], v[34:37]
	v_mfma_f32_16x16x32_bf16 v[22:25], v[146:149], v[196:199], v[22:25]
	v_mfma_f32_16x16x32_bf16 v[18:21], v[164:167], v[196:199], v[18:21]
	v_mfma_f32_16x16x32_bf16 v[6:9], v[146:149], v[204:207], v[6:9]
	v_mfma_f32_16x16x32_bf16 v[2:5], v[164:167], v[204:207], v[2:5]
	v_mfma_f32_16x16x32_bf16 v[54:57], v[150:153], v[184:187], v[54:57]
	v_mfma_f32_16x16x32_bf16 v[50:53], v[168:171], v[184:187], v[50:53]
	v_mfma_f32_16x16x32_bf16 v[38:41], v[150:153], v[192:195], v[38:41]
	v_mfma_f32_16x16x32_bf16 v[34:37], v[168:171], v[192:195], v[34:37]
	v_mfma_f32_16x16x32_bf16 v[22:25], v[150:153], v[200:203], v[22:25]
	v_mfma_f32_16x16x32_bf16 v[18:21], v[168:171], v[200:203], v[18:21]
	v_mfma_f32_16x16x32_bf16 v[6:9], v[150:153], v[208:211], v[6:9]
	v_mfma_f32_16x16x32_bf16 v[2:5], v[168:171], v[208:211], v[2:5]
	s_barrier
	s_setprio 0
	s_add_i32 s48, s48, 2
	s_add_u32 s46, s46, 0x1000
	s_addc_u32 s47, s47, 0
	s_add_u32 s36, s36, 0x100
	s_addc_u32 s37, s37, 0
	s_cmpk_gt_u32 s48, 0x7d
	s_cbranch_scc0 .LBB0_1004
	s_and_b64 vcc, exec, s[10:11]
	s_cbranch_vccz .LBB0_1007
	s_barrier

; __global__ void __launch_bounds__(512, 2) fwd_megakernel(Args a_unused) {
	.amdhsa_kernel _Z14fwd_megakernel4Args
		.amdhsa_group_segment_fixed_size 0
		.amdhsa_private_segment_fixed_size 0
		.amdhsa_kernarg_size 424
		.amdhsa_user_sgpr_count 2
		.amdhsa_user_sgpr_dispatch_ptr 0
		.amdhsa_user_sgpr_queue_ptr 0
		.amdhsa_user_sgpr_kernarg_segment_ptr 1
		.amdhsa_user_sgpr_dispatch_id 0
		.amdhsa_user_sgpr_kernarg_preload_length 0
		.amdhsa_user_sgpr_kernarg_preload_offset 0
		.amdhsa_user_sgpr_private_segment_size 0
		.amdhsa_uses_dynamic_stack 0
		.amdhsa_enable_private_segment 0
		.amdhsa_system_sgpr_workgroup_id_x 1
		.amdhsa_system_sgpr_workgroup_id_y 0
		.amdhsa_system_sgpr_workgroup_id_z 0
		.amdhsa_system_sgpr_workgroup_info 0
		.amdhsa_system_vgpr_workitem_id 2
		.amdhsa_next_free_vgpr 256
		.amdhsa_next_free_sgpr 102
		.amdhsa_accum_offset 256
		.amdhsa_reserve_vcc 1
		.amdhsa_float_round_mode_32 0
		.amdhsa_float_round_mode_16_64 0
		.amdhsa_float_denorm_mode_32 3
		.amdhsa_float_denorm_mode_16_64 3
		.amdhsa_dx10_clamp 1
		.amdhsa_ieee_mode 1
		.amdhsa_fp16_overflow 0
		.amdhsa_tg_split 0
		.amdhsa_exception_fp_ieee_invalid_op 0
		.amdhsa_exception_fp_denorm_src 0
		.amdhsa_exception_fp_ieee_div_zero 0
		.amdhsa_exception_fp_ieee_overflow 0
		.amdhsa_exception_fp_ieee_underflow 0
		.amdhsa_exception_fp_ieee_inexact 0
		.amdhsa_exception_int_div_zero 0
	.end_amdhsa_kernel

; __global__ void __launch_bounds__(512, 2) fwd_megakernel(Args a_unused) {
amdhsa.kernels:
  - .agpr_count:     0
    .args:
      - .offset:         0
        .size:           168
        .value_kind:     by_value
      - .offset:         168
        .size:           4
        .value_kind:     hidden_block_count_x
      - .offset:         172
        .size:           4
        .value_kind:     hidden_block_count_y
      - .offset:         176
        .size:           4
        .value_kind:     hidden_block_count_z
      - .offset:         180
        .size:           2
        .value_kind:     hidden_group_size_x
      - .offset:         182
        .size:           2
        .value_kind:     hidden_group_size_y
      - .offset:         184
        .size:           2
        .value_kind:     hidden_group_size_z
      - .offset:         186
        .size:           2
        .value_kind:     hidden_remainder_x
      - .offset:         188
        .size:           2
        .value_kind:     hidden_remainder_y
      - .offset:         190
        .size:           2
        .value_kind:     hidden_remainder_z
      - .offset:         208
        .size:           8
        .value_kind:     hidden_global_offset_x
      - .offset:         216
        .size:           8
        .value_kind:     hidden_global_offset_y
      - .offset:         224
        .size:           8
        .value_kind:     hidden_global_offset_z
      - .offset:         232
        .size:           2
        .value_kind:     hidden_grid_dims
      - .offset:         256
        .size:           8
        .value_kind:     hidden_multigrid_sync_arg
      - .offset:         288
        .size:           4
        .value_kind:     hidden_dynamic_lds_size
    .group_segment_fixed_size: 0
    .kernarg_segment_align: 8
    .kernarg_segment_size: 424
    .language:       OpenCL C
    .language_version:
      - 2
      - 0
    .max_flat_workgroup_size: 512
    .name:           _Z14fwd_megakernel4Args
    .private_segment_fixed_size: 0
    .sgpr_count:     108
    .sgpr_spill_count: 132
    .symbol:         _Z14fwd_megakernel4Args.kd
    .uniform_work_group_size: 1
    .uses_dynamic_stack: false
    .vgpr_count:     256
    .vgpr_spill_count: 0
    .wavefront_size: 64
